# GDN intra-chunk triangular solve: off-diagonal block updates on the f32 matrix cores (v_mfma_f32_16x16x4_f32), one column per lane for the diagonal blocks, wider u stores
# speedup vs baseline: 1.0370x; 1.0370x over previous
; #define LAS __attribute__((address_space(3)))
; __device__ __forceinline__ float bf2f(bf16_t h) { return __uint_as_float(((unsigned)h) << 16); }
; __device__ __forceinline__ bf16_t f2bf(float f) { return (bf16_t)(cvt_pk(f, 0.f) & 0xffffu); }
; __device__ __forceinline__ void gdn_intra_item(const Ctx& a, int l, int h, int c, LAS unsigned char* lds) {
;     ...
;     if (tid < 256) {
;         const int cc = tid, d = cc & 127;
;         LAS float* xc = vf + cc;
;         bf16_t* dst = (bf16_t*)(a.ws + B_GW) + (size_t)t0 * 512 + h * 128 + d;
;         bf16_t* dstu = (bf16_t*)(a.ws + B_GU) + ((size_t)((h * 128 + c) * 4 + (d >> 5)) * 2) * 1024 + (d & 31) * 16;
; #pragma unroll 1
;         for (int bs = 0; bs < 64; bs += 16) {
;             float acc[16];
;             if (cc < 128) {
; #pragma unroll
;                 for (int r = 0; r < 16; ++r) { const int i = bs + r; acc[r] = xc[i * 256] * be[i]; }
;             } else {
; #pragma unroll
;                 for (int r = 0; r < 16; ++r) { const int i = bs + r; acc[r] = bf2f(kb[i * 136 + d]) * rkv[i] * be[i] * eg[i]; }
;             }
; #pragma unroll 1
;             for (int j = 0; j < bs; j += 4) {
;                 const float x0 = xc[(j + 0) * 256], x1 = xc[(j + 1) * 256], x2 = xc[(j + 2) * 256], x3 = xc[(j + 3) * 256];
; #pragma unroll
;                 for (int r = 0; r < 16; ++r) {
;                     f32x4 av = *(const LAS f32x4*)(Am + (bs + r) * 68 + j);
;                     acc[r] -= av[0] * x0 + av[1] * x1 + av[2] * x2 + av[3] * x3;
;                 }
;             }
; #pragma unroll
;             for (int r = 0; r < 16; ++r) {
; #pragma unroll
;                 for (int c4 = 0; c4 < (r + 3) / 4; ++c4) {
;                     f32x4 av = *(const LAS f32x4*)(Am + (bs + r) * 68 + bs + c4 * 4);
; #pragma unroll
;                     for (int e = 0; e < 4; ++e) if (c4 * 4 + e < r) acc[r] -= av[e] * acc[c4 * 4 + e];
;                 }
;                 const int i = bs + r;
;                 xc[i * 256] = acc[r];
;                 { const int i32 = i & 31; const int offu = (i >> 5) * 1024 + ((i32 >> 2) & 1) * 512 + (i32 >> 3) * 4 + (i & 3);
;                   bf16_t* ob = (cc < 128) ? dstu : dst; ob[(cc < 128) ? offu : i * 512] = f2bf(acc[r]); }
;             }
;         }
.Lgi_entry:
	s_nop 7
	s_nop 3
	v_lshrrev_b32 v64, 6, v179
	s_and_b32 s0, s9, 3
	s_lshr_b32 s1, s9, 2
	v_readfirstlane_b32 s26, v64
	v_and_b32 v65, 15, v195
	v_lshrrev_b32 v66, 4, v195
	s_lshl_b32 s6, s26, 6
	v_add_u32 v63, s6, v195
	v_mul_u32_u24 v54, 272, v65
	v_lshl_add_u32 v54, v66, 2, v54
	v_add_u32 v54, 100352, v54
	v_lshlrev_b32 v55, 10, v66
	v_lshl_add_u32 v55, v65, 2, v55
	s_lshl_b32 s8, s26, 8
	v_add_u32 v55, s8, v55
	v_add_u32 v55, 34816, v55
	s_mul_i32 s8, s26, 0x1400
	s_add_u32 s8, s8, 0x1e000
	v_mul_u32_u24 v56, 80, v65
	v_lshl_add_u32 v56, v66, 4, v56
	v_add_u32 v56, s8, v56
	v_mul_u32_u24 v57, 80, v195
	v_add_u32 v57, s8, v57
	v_lshlrev_b32 v58, 2, v63
	v_add_u32 v58, 34816, v58
	v_mov_b32 v62, 0x18800
	s_cmp_ge_u32 s26, 2
	s_cbranch_scc1 .Lgi_W
	s_lshl_b32 s6, s0, 7
	s_add_u32 s6, s6, s1
	s_lshl_b32 s6, s6, 14
	s_add_u32 s36, s16, 0xe8f4200
	s_addc_u32 s37, s17, 0
	s_add_u32 s36, s36, s6
	s_addc_u32 s37, s37, 0
	v_lshrrev_b32 v64, 5, v63
	v_and_b32 v65, 31, v63
	v_lshlrev_b32 v60, 12, v64
	v_lshl_add_u32 v60, v65, 5, v60
	ds_read_b128 v[38:41], v62 offset:17664
	ds_read_b128 v[42:45], v62 offset:17680
	ds_read_b128 v[46:49], v62 offset:17696
	ds_read_b128 v[50:53], v62 offset:17712
	ds_read_b32 v68, v58 offset:0
	ds_read_b32 v69, v58 offset:1024
	ds_read_b32 v70, v58 offset:2048
	ds_read_b32 v71, v58 offset:3072
	ds_read_b32 v72, v58 offset:4096
	ds_read_b32 v73, v58 offset:5120
	ds_read_b32 v74, v58 offset:6144
	ds_read_b32 v75, v58 offset:7168
	ds_read_b32 v76, v58 offset:8192
	ds_read_b32 v77, v58 offset:9216
	ds_read_b32 v78, v58 offset:10240
	ds_read_b32 v79, v58 offset:11264
	ds_read_b32 v80, v58 offset:12288
	ds_read_b32 v81, v58 offset:13312
	ds_read_b32 v82, v58 offset:14336
	ds_read_b32 v83, v58 offset:15360
	s_waitcnt lgkmcnt(15)
	v_mul_f32 v68, v68, v38
	s_waitcnt lgkmcnt(14)
	v_mul_f32 v69, v69, v39
	s_waitcnt lgkmcnt(13)
	v_mul_f32 v70, v70, v40
	s_waitcnt lgkmcnt(12)
	v_mul_f32 v71, v71, v41
	s_waitcnt lgkmcnt(11)
	v_mul_f32 v72, v72, v42
	s_waitcnt lgkmcnt(10)
	v_mul_f32 v73, v73, v43
	s_waitcnt lgkmcnt(9)
	v_mul_f32 v74, v74, v44
	s_waitcnt lgkmcnt(8)
	v_mul_f32 v75, v75, v45
	s_waitcnt lgkmcnt(7)
	v_mul_f32 v76, v76, v46
	s_waitcnt lgkmcnt(6)
	v_mul_f32 v77, v77, v47
	s_waitcnt lgkmcnt(5)
	v_mul_f32 v78, v78, v48
	s_waitcnt lgkmcnt(4)
	v_mul_f32 v79, v79, v49
	s_waitcnt lgkmcnt(3)
	v_mul_f32 v80, v80, v50
	s_waitcnt lgkmcnt(2)
	v_mul_f32 v81, v81, v51
	s_waitcnt lgkmcnt(1)
	v_mul_f32 v82, v82, v52
	s_waitcnt lgkmcnt(0)
	v_mul_f32 v83, v83, v53
	ds_read_b128 v[38:41], v62 offset:272
	ds_read_b128 v[20:23], v62 offset:544
	s_waitcnt lgkmcnt(1)
	v_fma_f32 v69, -v38, v68, v69
	ds_read_b128 v[38:41], v62 offset:816
	s_waitcnt lgkmcnt(1)
	v_fma_f32 v70, -v20, v68, v70
	v_fma_f32 v70, -v21, v69, v70
	ds_read_b128 v[20:23], v62 offset:1088
	s_waitcnt lgkmcnt(1)
	v_fma_f32 v71, -v38, v68, v71
	v_fma_f32 v71, -v39, v69, v71
	v_fma_f32 v71, -v40, v70, v71
	ds_read_b128 v[38:41], v62 offset:1360
	ds_read_b128 v[42:45], v62 offset:1376
	s_waitcnt lgkmcnt(2)
	v_fma_f32 v72, -v20, v68, v72
	v_fma_f32 v72, -v21, v69, v72
	v_fma_f32 v72, -v22, v70, v72
	v_fma_f32 v72, -v23, v71, v72
	ds_read_b128 v[20:23], v62 offset:1632
	ds_read_b128 v[24:27], v62 offset:1648
	s_waitcnt lgkmcnt(3)
	v_fma_f32 v73, -v38, v68, v73
	v_fma_f32 v73, -v39, v69, v73
	v_fma_f32 v73, -v40, v70, v73
	v_fma_f32 v73, -v41, v71, v73
	s_waitcnt lgkmcnt(2)
	v_fma_f32 v73, -v42, v72, v73
	ds_read_b128 v[38:41], v62 offset:1904
	ds_read_b128 v[42:45], v62 offset:1920
	s_waitcnt lgkmcnt(3)
	v_fma_f32 v74, -v20, v68, v74
	v_fma_f32 v74, -v21, v69, v74
	v_fma_f32 v74, -v22, v70, v74
	v_fma_f32 v74, -v23, v71, v74
	s_waitcnt lgkmcnt(2)
	v_fma_f32 v74, -v24, v72, v74
	v_fma_f32 v74, -v25, v73, v74
	ds_read_b128 v[20:23], v62 offset:2176
	ds_read_b128 v[24:27], v62 offset:2192
	s_waitcnt lgkmcnt(3)
	v_fma_f32 v75, -v38, v68, v75
	v_fma_f32 v75, -v39, v69, v75
	v_fma_f32 v75, -v40, v70, v75
	v_fma_f32 v75, -v41, v71, v75
	s_waitcnt lgkmcnt(2)
	v_fma_f32 v75, -v42, v72, v75
	v_fma_f32 v75, -v43, v73, v75
	v_fma_f32 v75, -v44, v74, v75
	ds_read_b128 v[38:41], v62 offset:2448
	ds_read_b128 v[42:45], v62 offset:2464
	ds_read_b128 v[46:49], v62 offset:2480
	s_waitcnt lgkmcnt(4)
	v_fma_f32 v76, -v20, v68, v76
	v_fma_f32 v76, -v21, v69, v76
	v_fma_f32 v76, -v22, v70, v76
	v_fma_f32 v76, -v23, v71, v76
	s_waitcnt lgkmcnt(3)
	v_fma_f32 v76, -v24, v72, v76
	v_fma_f32 v76, -v25, v73, v76
	v_fma_f32 v76, -v26, v74, v76
	v_fma_f32 v76, -v27, v75, v76
	ds_read_b128 v[20:23], v62 offset:2720
	ds_read_b128 v[24:27], v62 offset:2736
	ds_read_b128 v[28:31], v62 offset:2752
	s_waitcnt lgkmcnt(5)
	v_fma_f32 v77, -v38, v68, v77
	v_fma_f32 v77, -v39, v69, v77
	v_fma_f32 v77, -v40, v70, v77
	v_fma_f32 v77, -v41, v71, v77
	s_waitcnt lgkmcnt(4)
	v_fma_f32 v77, -v42, v72, v77
	v_fma_f32 v77, -v43, v73, v77
	v_fma_f32 v77, -v44, v74, v77
	v_fma_f32 v77, -v45, v75, v77
	s_waitcnt lgkmcnt(3)
	v_fma_f32 v77, -v46, v76, v77
	ds_read_b128 v[38:41], v62 offset:2992
	ds_read_b128 v[42:45], v62 offset:3008
	ds_read_b128 v[46:49], v62 offset:3024
	s_waitcnt lgkmcnt(5)
	v_fma_f32 v78, -v20, v68, v78
	v_fma_f32 v78, -v21, v69, v78
	v_fma_f32 v78, -v22, v70, v78
	v_fma_f32 v78, -v23, v71, v78
	s_waitcnt lgkmcnt(4)
	v_fma_f32 v78, -v24, v72, v78
	v_fma_f32 v78, -v25, v73, v78
	v_fma_f32 v78, -v26, v74, v78
	v_fma_f32 v78, -v27, v75, v78
	s_waitcnt lgkmcnt(3)
	v_fma_f32 v78, -v28, v76, v78
	v_fma_f32 v78, -v29, v77, v78
	ds_read_b128 v[20:23], v62 offset:3264
	ds_read_b128 v[24:27], v62 offset:3280
	ds_read_b128 v[28:31], v62 offset:3296
	s_waitcnt lgkmcnt(5)
; #define LAS __attribute__((address_space(3)))
; __device__ __forceinline__ float bf2f(bf16_t h) { return __uint_as_float(((unsigned)h) << 16); }
; __device__ __forceinline__ bf16_t f2bf(float f) { return (bf16_t)(cvt_pk(f, 0.f) & 0xffffu); }
; __device__ __forceinline__ void gdn_intra_item(const Ctx& a, int l, int h, int c, LAS unsigned char* lds) {
;     ...
;     if (tid < 256) {
;         const int cc = tid, d = cc & 127;
;         LAS float* xc = vf + cc;
;         bf16_t* dst = (bf16_t*)(a.ws + B_GW) + (size_t)t0 * 512 + h * 128 + d;
;         bf16_t* dstu = (bf16_t*)(a.ws + B_GU) + ((size_t)((h * 128 + c) * 4 + (d >> 5)) * 2) * 1024 + (d & 31) * 16;
; #pragma unroll 1
;         for (int bs = 0; bs < 64; bs += 16) {
;             float acc[16];
;             if (cc < 128) {
; #pragma unroll
;                 for (int r = 0; r < 16; ++r) { const int i = bs + r; acc[r] = xc[i * 256] * be[i]; }
;             } else {
; #pragma unroll
;                 for (int r = 0; r < 16; ++r) { const int i = bs + r; acc[r] = bf2f(kb[i * 136 + d]) * rkv[i] * be[i] * eg[i]; }
;             }
; #pragma unroll 1
;             for (int j = 0; j < bs; j += 4) {
;                 const float x0 = xc[(j + 0) * 256], x1 = xc[(j + 1) * 256], x2 = xc[(j + 2) * 256], x3 = xc[(j + 3) * 256];
; #pragma unroll
;                 for (int r = 0; r < 16; ++r) {
;                     f32x4 av = *(const LAS f32x4*)(Am + (bs + r) * 68 + j);
;                     acc[r] -= av[0] * x0 + av[1] * x1 + av[2] * x2 + av[3] * x3;
;                 }
;             }
; #pragma unroll
;             for (int r = 0; r < 16; ++r) {
; #pragma unroll
;                 for (int c4 = 0; c4 < (r + 3) / 4; ++c4) {
;                     f32x4 av = *(const LAS f32x4*)(Am + (bs + r) * 68 + bs + c4 * 4);
; #pragma unroll
;                     for (int e = 0; e < 4; ++e) if (c4 * 4 + e < r) acc[r] -= av[e] * acc[c4 * 4 + e];
;                 }
;                 const int i = bs + r;
;                 xc[i * 256] = acc[r];
;                 { const int i32 = i & 31; const int offu = (i >> 5) * 1024 + ((i32 >> 2) & 1) * 512 + (i32 >> 3) * 4 + (i & 3);
;                   bf16_t* ob = (cc < 128) ? dstu : dst; ob[(cc < 128) ? offu : i * 512] = f2bf(acc[r]); }
;             }
;         }
	v_fma_f32 v79, -v38, v68, v79
	v_fma_f32 v79, -v39, v69, v79
	v_fma_f32 v79, -v40, v70, v79
	v_fma_f32 v79, -v41, v71, v79
	s_waitcnt lgkmcnt(4)
	v_fma_f32 v79, -v42, v72, v79
	v_fma_f32 v79, -v43, v73, v79
	v_fma_f32 v79, -v44, v74, v79
	v_fma_f32 v79, -v45, v75, v79
	s_waitcnt lgkmcnt(3)
	v_fma_f32 v79, -v46, v76, v79
	v_fma_f32 v79, -v47, v77, v79
	v_fma_f32 v79, -v48, v78, v79
	ds_read_b128 v[38:41], v62 offset:3536
	ds_read_b128 v[42:45], v62 offset:3552
	ds_read_b128 v[46:49], v62 offset:3568
	ds_read_b128 v[50:53], v62 offset:3584
	s_waitcnt lgkmcnt(6)
	v_fma_f32 v80, -v20, v68, v80
	v_fma_f32 v80, -v21, v69, v80
	v_fma_f32 v80, -v22, v70, v80
	v_fma_f32 v80, -v23, v71, v80
	s_waitcnt lgkmcnt(5)
	v_fma_f32 v80, -v24, v72, v80
	v_fma_f32 v80, -v25, v73, v80
	v_fma_f32 v80, -v26, v74, v80
	v_fma_f32 v80, -v27, v75, v80
	s_waitcnt lgkmcnt(4)
	v_fma_f32 v80, -v28, v76, v80
	v_fma_f32 v80, -v29, v77, v80
	v_fma_f32 v80, -v30, v78, v80
	v_fma_f32 v80, -v31, v79, v80
	ds_read_b128 v[20:23], v62 offset:3808
	ds_read_b128 v[24:27], v62 offset:3824
	ds_read_b128 v[28:31], v62 offset:3840
	ds_read_b128 v[32:35], v62 offset:3856
	s_waitcnt lgkmcnt(7)
	v_fma_f32 v81, -v38, v68, v81
	v_fma_f32 v81, -v39, v69, v81
	v_fma_f32 v81, -v40, v70, v81
	v_fma_f32 v81, -v41, v71, v81
	s_waitcnt lgkmcnt(6)
	v_fma_f32 v81, -v42, v72, v81
	v_fma_f32 v81, -v43, v73, v81
	v_fma_f32 v81, -v44, v74, v81
	v_fma_f32 v81, -v45, v75, v81
	s_waitcnt lgkmcnt(5)
	v_fma_f32 v81, -v46, v76, v81
	v_fma_f32 v81, -v47, v77, v81
	v_fma_f32 v81, -v48, v78, v81
	v_fma_f32 v81, -v49, v79, v81
	s_waitcnt lgkmcnt(4)
	v_fma_f32 v81, -v50, v80, v81
	ds_read_b128 v[38:41], v62 offset:4080
	ds_read_b128 v[42:45], v62 offset:4096
	ds_read_b128 v[46:49], v62 offset:4112
	ds_read_b128 v[50:53], v62 offset:4128
	s_waitcnt lgkmcnt(7)
	v_fma_f32 v82, -v20, v68, v82
	v_fma_f32 v82, -v21, v69, v82
	v_fma_f32 v82, -v22, v70, v82
	v_fma_f32 v82, -v23, v71, v82
	s_waitcnt lgkmcnt(6)
	v_fma_f32 v82, -v24, v72, v82
	v_fma_f32 v82, -v25, v73, v82
	v_fma_f32 v82, -v26, v74, v82
	v_fma_f32 v82, -v27, v75, v82
	s_waitcnt lgkmcnt(5)
	v_fma_f32 v82, -v28, v76, v82
	v_fma_f32 v82, -v29, v77, v82
	v_fma_f32 v82, -v30, v78, v82
	v_fma_f32 v82, -v31, v79, v82
	s_waitcnt lgkmcnt(4)
	v_fma_f32 v82, -v32, v80, v82
	v_fma_f32 v82, -v33, v81, v82
	s_waitcnt lgkmcnt(3)
	v_fma_f32 v83, -v38, v68, v83
	v_fma_f32 v83, -v39, v69, v83
	v_fma_f32 v83, -v40, v70, v83
	v_fma_f32 v83, -v41, v71, v83
	s_waitcnt lgkmcnt(2)
	v_fma_f32 v83, -v42, v72, v83
	v_fma_f32 v83, -v43, v73, v83
	v_fma_f32 v83, -v44, v74, v83
	v_fma_f32 v83, -v45, v75, v83
	s_waitcnt lgkmcnt(1)
	v_fma_f32 v83, -v46, v76, v83
	v_fma_f32 v83, -v47, v77, v83
	v_fma_f32 v83, -v48, v78, v83
	v_fma_f32 v83, -v49, v79, v83
	s_waitcnt lgkmcnt(0)
	v_fma_f32 v83, -v50, v80, v83
	v_fma_f32 v83, -v51, v81, v83
	v_fma_f32 v83, -v52, v82, v83
	ds_write_b32 v58, v68 offset:0
	ds_write_b32 v58, v69 offset:1024
	ds_write_b32 v58, v70 offset:2048
	ds_write_b32 v58, v71 offset:3072
	ds_write_b32 v58, v72 offset:4096
	ds_write_b32 v58, v73 offset:5120
	ds_write_b32 v58, v74 offset:6144
	ds_write_b32 v58, v75 offset:7168
	ds_write_b32 v58, v76 offset:8192
	ds_write_b32 v58, v77 offset:9216
	ds_write_b32 v58, v78 offset:10240
	ds_write_b32 v58, v79 offset:11264
	ds_write_b32 v58, v80 offset:12288
	ds_write_b32 v58, v81 offset:13312
	ds_write_b32 v58, v82 offset:14336
	ds_write_b32 v58, v83 offset:15360
	v_cvt_pk_bf16_f32 v2, v68, v69
	v_cvt_pk_bf16_f32 v3, v70, v71
	v_cvt_pk_bf16_f32 v4, v76, v77
	v_cvt_pk_bf16_f32 v5, v78, v79
	global_store_dwordx4 v60, v[2:5], s[36:37] offset:0
	v_cvt_pk_bf16_f32 v6, v72, v73
	v_cvt_pk_bf16_f32 v7, v74, v75
	v_cvt_pk_bf16_f32 v8, v80, v81
	v_cvt_pk_bf16_f32 v9, v82, v83
	global_store_dwordx4 v60, v[6:9], s[36:37] offset:1024
	ds_read_b32 v36, v54 offset:4352
	ds_read_b32 v38, v55 offset:0
	ds_read_b32 v39, v55 offset:64
	ds_read_b32 v40, v55 offset:128
	ds_read_b32 v41, v55 offset:192
	ds_read_b32 v19, v54 offset:4368
	ds_read_b32 v42, v55 offset:4096
	ds_read_b32 v43, v55 offset:4160
	ds_read_b32 v44, v55 offset:4224
	ds_read_b32 v45, v55 offset:4288
	s_waitcnt lgkmcnt(8)
	v_mfma_f32_16x16x4_f32 v[20:23], v36, v38, 0
	s_waitcnt lgkmcnt(7)
	v_mfma_f32_16x16x4_f32 v[24:27], v36, v39, 0
	s_waitcnt lgkmcnt(6)
	v_mfma_f32_16x16x4_f32 v[28:31], v36, v40, 0
	s_waitcnt lgkmcnt(5)
	v_mfma_f32_16x16x4_f32 v[32:35], v36, v41, 0
	ds_read_b32 v36, v54 offset:4384
	ds_read_b32 v38, v55 offset:8192
	ds_read_b32 v39, v55 offset:8256
	ds_read_b32 v40, v55 offset:8320
	ds_read_b32 v41, v55 offset:8384
	s_waitcnt lgkmcnt(8)
	v_mfma_f32_16x16x4_f32 v[20:23], v19, v42, v[20:23]
	s_waitcnt lgkmcnt(7)
	v_mfma_f32_16x16x4_f32 v[24:27], v19, v43, v[24:27]
	s_waitcnt lgkmcnt(6)
	v_mfma_f32_16x16x4_f32 v[28:31], v19, v44, v[28:31]
	s_waitcnt lgkmcnt(5)
	v_mfma_f32_16x16x4_f32 v[32:35], v19, v45, v[32:35]
	ds_read_b32 v19, v54 offset:4400
	ds_read_b32 v42, v55 offset:12288
	ds_read_b32 v43, v55 offset:12352
	ds_read_b32 v44, v55 offset:12416
	ds_read_b32 v45, v55 offset:12480
	s_waitcnt lgkmcnt(8)
	v_mfma_f32_16x16x4_f32 v[20:23], v36, v38, v[20:23]
	s_waitcnt lgkmcnt(7)
	v_mfma_f32_16x16x4_f32 v[24:27], v36, v39, v[24:27]
	s_waitcnt lgkmcnt(6)
	v_mfma_f32_16x16x4_f32 v[28:31], v36, v40, v[28:31]
	s_waitcnt lgkmcnt(5)
	v_mfma_f32_16x16x4_f32 v[32:35], v36, v41, v[32:35]
	s_waitcnt lgkmcnt(3)
	v_mfma_f32_16x16x4_f32 v[20:23], v19, v42, v[20:23]
	s_waitcnt lgkmcnt(2)
	v_mfma_f32_16x16x4_f32 v[24:27], v19, v43, v[24:27]
	s_waitcnt lgkmcnt(1)
	v_mfma_f32_16x16x4_f32 v[28:31], v19, v44, v[28:31]
	s_waitcnt lgkmcnt(0)
; #define LAS __attribute__((address_space(3)))
; __device__ __forceinline__ float bf2f(bf16_t h) { return __uint_as_float(((unsigned)h) << 16); }
; __device__ __forceinline__ bf16_t f2bf(float f) { return (bf16_t)(cvt_pk(f, 0.f) & 0xffffu); }
; __device__ __forceinline__ void gdn_intra_item(const Ctx& a, int l, int h, int c, LAS unsigned char* lds) {
;     ...
;     if (tid < 256) {
;         const int cc = tid, d = cc & 127;
;         LAS float* xc = vf + cc;
;         bf16_t* dst = (bf16_t*)(a.ws + B_GW) + (size_t)t0 * 512 + h * 128 + d;
;         bf16_t* dstu = (bf16_t*)(a.ws + B_GU) + ((size_t)((h * 128 + c) * 4 + (d >> 5)) * 2) * 1024 + (d & 31) * 16;
; #pragma unroll 1
;         for (int bs = 0; bs < 64; bs += 16) {
;             float acc[16];
;             if (cc < 128) {
; #pragma unroll
;                 for (int r = 0; r < 16; ++r) { const int i = bs + r; acc[r] = xc[i * 256] * be[i]; }
;             } else {
; #pragma unroll
;                 for (int r = 0; r < 16; ++r) { const int i = bs + r; acc[r] = bf2f(kb[i * 136 + d]) * rkv[i] * be[i] * eg[i]; }
;             }
; #pragma unroll 1
;             for (int j = 0; j < bs; j += 4) {
;                 const float x0 = xc[(j + 0) * 256], x1 = xc[(j + 1) * 256], x2 = xc[(j + 2) * 256], x3 = xc[(j + 3) * 256];
; #pragma unroll
;                 for (int r = 0; r < 16; ++r) {
;                     f32x4 av = *(const LAS f32x4*)(Am + (bs + r) * 68 + j);
;                     acc[r] -= av[0] * x0 + av[1] * x1 + av[2] * x2 + av[3] * x3;
;                 }
;             }
; #pragma unroll
;             for (int r = 0; r < 16; ++r) {
; #pragma unroll
;                 for (int c4 = 0; c4 < (r + 3) / 4; ++c4) {
;                     f32x4 av = *(const LAS f32x4*)(Am + (bs + r) * 68 + bs + c4 * 4);
; #pragma unroll
;                     for (int e = 0; e < 4; ++e) if (c4 * 4 + e < r) acc[r] -= av[e] * acc[c4 * 4 + e];
;                 }
;                 const int i = bs + r;
;                 xc[i * 256] = acc[r];
;                 { const int i32 = i & 31; const int offu = (i >> 5) * 1024 + ((i32 >> 2) & 1) * 512 + (i32 >> 3) * 4 + (i & 3);
;                   bf16_t* ob = (cc < 128) ? dstu : dst; ob[(cc < 128) ? offu : i * 512] = f2bf(acc[r]); }
;             }
;         }
	v_mfma_f32_16x16x4_f32 v[32:35], v19, v45, v[32:35]
	s_nop 5
	ds_write_b128 v56, v[20:23] offset:0
	s_nop 0
	ds_write_b128 v56, v[24:27] offset:1280
	s_nop 0
	ds_write_b128 v56, v[28:31] offset:2560
	s_nop 0
	ds_write_b128 v56, v[32:35] offset:3840
	ds_read_b128 v[2:5], v57 offset:0
	ds_read_b128 v[6:9], v57 offset:16
	ds_read_b128 v[10:13], v57 offset:32
	ds_read_b128 v[14:17], v57 offset:48
	ds_read_b128 v[38:41], v62 offset:17728
	ds_read_b128 v[42:45], v62 offset:17744
	ds_read_b128 v[46:49], v62 offset:17760
	ds_read_b128 v[50:53], v62 offset:17776
	ds_read_b32 v68, v58 offset:16384
	ds_read_b32 v69, v58 offset:17408
	ds_read_b32 v70, v58 offset:18432
	ds_read_b32 v71, v58 offset:19456
	ds_read_b32 v72, v58 offset:20480
	ds_read_b32 v73, v58 offset:21504
	ds_read_b32 v74, v58 offset:22528
	ds_read_b32 v75, v58 offset:23552
	ds_read_b32 v76, v58 offset:24576
	ds_read_b32 v77, v58 offset:25600
	ds_read_b32 v78, v58 offset:26624
	ds_read_b32 v79, v58 offset:27648
	ds_read_b32 v80, v58 offset:28672
	ds_read_b32 v81, v58 offset:29696
	ds_read_b32 v82, v58 offset:30720
	ds_read_b32 v83, v58 offset:31744
	s_waitcnt lgkmcnt(15)
	v_fma_f32 v68, v68, v38, -v2
	s_waitcnt lgkmcnt(14)
	v_fma_f32 v69, v69, v39, -v3
	s_waitcnt lgkmcnt(13)
	v_fma_f32 v70, v70, v40, -v4
	s_waitcnt lgkmcnt(12)
	v_fma_f32 v71, v71, v41, -v5
	s_waitcnt lgkmcnt(11)
	v_fma_f32 v72, v72, v42, -v6
	s_waitcnt lgkmcnt(10)
	v_fma_f32 v73, v73, v43, -v7
	s_waitcnt lgkmcnt(9)
	v_fma_f32 v74, v74, v44, -v8
	s_waitcnt lgkmcnt(8)
	v_fma_f32 v75, v75, v45, -v9
	s_waitcnt lgkmcnt(7)
	v_fma_f32 v76, v76, v46, -v10
	s_waitcnt lgkmcnt(6)
	v_fma_f32 v77, v77, v47, -v11
	s_waitcnt lgkmcnt(5)
	v_fma_f32 v78, v78, v48, -v12
	s_waitcnt lgkmcnt(4)
	v_fma_f32 v79, v79, v49, -v13
	s_waitcnt lgkmcnt(3)
	v_fma_f32 v80, v80, v50, -v14
	s_waitcnt lgkmcnt(2)
	v_fma_f32 v81, v81, v51, -v15
	s_waitcnt lgkmcnt(1)
	v_fma_f32 v82, v82, v52, -v16
	s_waitcnt lgkmcnt(0)
	v_fma_f32 v83, v83, v53, -v17
	ds_read_b128 v[38:41], v62 offset:4688
	ds_read_b128 v[20:23], v62 offset:4960
	s_waitcnt lgkmcnt(1)
	v_fma_f32 v69, -v38, v68, v69
	ds_read_b128 v[38:41], v62 offset:5232
	s_waitcnt lgkmcnt(1)
	v_fma_f32 v70, -v20, v68, v70
	v_fma_f32 v70, -v21, v69, v70
	ds_read_b128 v[20:23], v62 offset:5504
	s_waitcnt lgkmcnt(1)
	v_fma_f32 v71, -v38, v68, v71
	v_fma_f32 v71, -v39, v69, v71
	v_fma_f32 v71, -v40, v70, v71
	ds_read_b128 v[38:41], v62 offset:5776
	ds_read_b128 v[42:45], v62 offset:5792
	s_waitcnt lgkmcnt(2)
	v_fma_f32 v72, -v20, v68, v72
	v_fma_f32 v72, -v21, v69, v72
	v_fma_f32 v72, -v22, v70, v72
	v_fma_f32 v72, -v23, v71, v72
	ds_read_b128 v[20:23], v62 offset:6048
	ds_read_b128 v[24:27], v62 offset:6064
	s_waitcnt lgkmcnt(3)
	v_fma_f32 v73, -v38, v68, v73
	v_fma_f32 v73, -v39, v69, v73
	v_fma_f32 v73, -v40, v70, v73
	v_fma_f32 v73, -v41, v71, v73
	s_waitcnt lgkmcnt(2)
	v_fma_f32 v73, -v42, v72, v73
	ds_read_b128 v[38:41], v62 offset:6320
	ds_read_b128 v[42:45], v62 offset:6336
	s_waitcnt lgkmcnt(3)
	v_fma_f32 v74, -v20, v68, v74
	v_fma_f32 v74, -v21, v69, v74
	v_fma_f32 v74, -v22, v70, v74
	v_fma_f32 v74, -v23, v71, v74
	s_waitcnt lgkmcnt(2)
	v_fma_f32 v74, -v24, v72, v74
	v_fma_f32 v74, -v25, v73, v74
	ds_read_b128 v[20:23], v62 offset:6592
	ds_read_b128 v[24:27], v62 offset:6608
	s_waitcnt lgkmcnt(3)
	v_fma_f32 v75, -v38, v68, v75
	v_fma_f32 v75, -v39, v69, v75
	v_fma_f32 v75, -v40, v70, v75
	v_fma_f32 v75, -v41, v71, v75
	s_waitcnt lgkmcnt(2)
	v_fma_f32 v75, -v42, v72, v75
	v_fma_f32 v75, -v43, v73, v75
	v_fma_f32 v75, -v44, v74, v75
	ds_read_b128 v[38:41], v62 offset:6864
	ds_read_b128 v[42:45], v62 offset:6880
	ds_read_b128 v[46:49], v62 offset:6896
	s_waitcnt lgkmcnt(4)
	v_fma_f32 v76, -v20, v68, v76
	v_fma_f32 v76, -v21, v69, v76
	v_fma_f32 v76, -v22, v70, v76
	v_fma_f32 v76, -v23, v71, v76
	s_waitcnt lgkmcnt(3)
	v_fma_f32 v76, -v24, v72, v76
	v_fma_f32 v76, -v25, v73, v76
	v_fma_f32 v76, -v26, v74, v76
	v_fma_f32 v76, -v27, v75, v76
	ds_read_b128 v[20:23], v62 offset:7136
	ds_read_b128 v[24:27], v62 offset:7152
	ds_read_b128 v[28:31], v62 offset:7168
	s_waitcnt lgkmcnt(5)
	v_fma_f32 v77, -v38, v68, v77
	v_fma_f32 v77, -v39, v69, v77
	v_fma_f32 v77, -v40, v70, v77
	v_fma_f32 v77, -v41, v71, v77
	s_waitcnt lgkmcnt(4)
	v_fma_f32 v77, -v42, v72, v77
	v_fma_f32 v77, -v43, v73, v77
	v_fma_f32 v77, -v44, v74, v77
	v_fma_f32 v77, -v45, v75, v77
	s_waitcnt lgkmcnt(3)
	v_fma_f32 v77, -v46, v76, v77
	ds_read_b128 v[38:41], v62 offset:7408
	ds_read_b128 v[42:45], v62 offset:7424
	ds_read_b128 v[46:49], v62 offset:7440
	s_waitcnt lgkmcnt(5)
	v_fma_f32 v78, -v20, v68, v78
	v_fma_f32 v78, -v21, v69, v78
	v_fma_f32 v78, -v22, v70, v78
	v_fma_f32 v78, -v23, v71, v78
	s_waitcnt lgkmcnt(4)
	v_fma_f32 v78, -v24, v72, v78
	v_fma_f32 v78, -v25, v73, v78
	v_fma_f32 v78, -v26, v74, v78
	v_fma_f32 v78, -v27, v75, v78
	s_waitcnt lgkmcnt(3)
	v_fma_f32 v78, -v28, v76, v78
	v_fma_f32 v78, -v29, v77, v78
	ds_read_b128 v[20:23], v62 offset:7680
	ds_read_b128 v[24:27], v62 offset:7696
	ds_read_b128 v[28:31], v62 offset:7712
	s_waitcnt lgkmcnt(5)
	v_fma_f32 v79, -v38, v68, v79
	v_fma_f32 v79, -v39, v69, v79
	v_fma_f32 v79, -v40, v70, v79
	v_fma_f32 v79, -v41, v71, v79
	s_waitcnt lgkmcnt(4)
	v_fma_f32 v79, -v42, v72, v79
	v_fma_f32 v79, -v43, v73, v79
	v_fma_f32 v79, -v44, v74, v79
	v_fma_f32 v79, -v45, v75, v79
	s_waitcnt lgkmcnt(3)
	v_fma_f32 v79, -v46, v76, v79
	v_fma_f32 v79, -v47, v77, v79
	v_fma_f32 v79, -v48, v78, v79
	ds_read_b128 v[38:41], v62 offset:7952
	ds_read_b128 v[42:45], v62 offset:7968
	ds_read_b128 v[46:49], v62 offset:7984
	ds_read_b128 v[50:53], v62 offset:8000
	s_waitcnt lgkmcnt(6)
; #define LAS __attribute__((address_space(3)))
; __device__ __forceinline__ float bf2f(bf16_t h) { return __uint_as_float(((unsigned)h) << 16); }
; __device__ __forceinline__ bf16_t f2bf(float f) { return (bf16_t)(cvt_pk(f, 0.f) & 0xffffu); }
; __device__ __forceinline__ void gdn_intra_item(const Ctx& a, int l, int h, int c, LAS unsigned char* lds) {
;     ...
;     if (tid < 256) {
;         const int cc = tid, d = cc & 127;
;         LAS float* xc = vf + cc;
;         bf16_t* dst = (bf16_t*)(a.ws + B_GW) + (size_t)t0 * 512 + h * 128 + d;
;         bf16_t* dstu = (bf16_t*)(a.ws + B_GU) + ((size_t)((h * 128 + c) * 4 + (d >> 5)) * 2) * 1024 + (d & 31) * 16;
; #pragma unroll 1
;         for (int bs = 0; bs < 64; bs += 16) {
;             float acc[16];
;             if (cc < 128) {
; #pragma unroll
;                 for (int r = 0; r < 16; ++r) { const int i = bs + r; acc[r] = xc[i * 256] * be[i]; }
;             } else {
; #pragma unroll
;                 for (int r = 0; r < 16; ++r) { const int i = bs + r; acc[r] = bf2f(kb[i * 136 + d]) * rkv[i] * be[i] * eg[i]; }
;             }
; #pragma unroll 1
;             for (int j = 0; j < bs; j += 4) {
;                 const float x0 = xc[(j + 0) * 256], x1 = xc[(j + 1) * 256], x2 = xc[(j + 2) * 256], x3 = xc[(j + 3) * 256];
; #pragma unroll
;                 for (int r = 0; r < 16; ++r) {
;                     f32x4 av = *(const LAS f32x4*)(Am + (bs + r) * 68 + j);
;                     acc[r] -= av[0] * x0 + av[1] * x1 + av[2] * x2 + av[3] * x3;
;                 }
;             }
; #pragma unroll
;             for (int r = 0; r < 16; ++r) {
; #pragma unroll
;                 for (int c4 = 0; c4 < (r + 3) / 4; ++c4) {
;                     f32x4 av = *(const LAS f32x4*)(Am + (bs + r) * 68 + bs + c4 * 4);
; #pragma unroll
;                     for (int e = 0; e < 4; ++e) if (c4 * 4 + e < r) acc[r] -= av[e] * acc[c4 * 4 + e];
;                 }
;                 const int i = bs + r;
;                 xc[i * 256] = acc[r];
;                 { const int i32 = i & 31; const int offu = (i >> 5) * 1024 + ((i32 >> 2) & 1) * 512 + (i32 >> 3) * 4 + (i & 3);
;                   bf16_t* ob = (cc < 128) ? dstu : dst; ob[(cc < 128) ? offu : i * 512] = f2bf(acc[r]); }
;             }
;         }
	v_fma_f32 v80, -v20, v68, v80
	v_fma_f32 v80, -v21, v69, v80
	v_fma_f32 v80, -v22, v70, v80
	v_fma_f32 v80, -v23, v71, v80
	s_waitcnt lgkmcnt(5)
	v_fma_f32 v80, -v24, v72, v80
	v_fma_f32 v80, -v25, v73, v80
	v_fma_f32 v80, -v26, v74, v80
	v_fma_f32 v80, -v27, v75, v80
	s_waitcnt lgkmcnt(4)
	v_fma_f32 v80, -v28, v76, v80
	v_fma_f32 v80, -v29, v77, v80
	v_fma_f32 v80, -v30, v78, v80
	v_fma_f32 v80, -v31, v79, v80
	ds_read_b128 v[20:23], v62 offset:8224
	ds_read_b128 v[24:27], v62 offset:8240
	ds_read_b128 v[28:31], v62 offset:8256
	ds_read_b128 v[32:35], v62 offset:8272
	s_waitcnt lgkmcnt(7)
	v_fma_f32 v81, -v38, v68, v81
	v_fma_f32 v81, -v39, v69, v81
	v_fma_f32 v81, -v40, v70, v81
	v_fma_f32 v81, -v41, v71, v81
	s_waitcnt lgkmcnt(6)
	v_fma_f32 v81, -v42, v72, v81
	v_fma_f32 v81, -v43, v73, v81
	v_fma_f32 v81, -v44, v74, v81
	v_fma_f32 v81, -v45, v75, v81
	s_waitcnt lgkmcnt(5)
	v_fma_f32 v81, -v46, v76, v81
	v_fma_f32 v81, -v47, v77, v81
	v_fma_f32 v81, -v48, v78, v81
	v_fma_f32 v81, -v49, v79, v81
	s_waitcnt lgkmcnt(4)
	v_fma_f32 v81, -v50, v80, v81
	ds_read_b128 v[38:41], v62 offset:8496
	ds_read_b128 v[42:45], v62 offset:8512
	ds_read_b128 v[46:49], v62 offset:8528
	ds_read_b128 v[50:53], v62 offset:8544
	s_waitcnt lgkmcnt(7)
	v_fma_f32 v82, -v20, v68, v82
	v_fma_f32 v82, -v21, v69, v82
	v_fma_f32 v82, -v22, v70, v82
	v_fma_f32 v82, -v23, v71, v82
	s_waitcnt lgkmcnt(6)
	v_fma_f32 v82, -v24, v72, v82
	v_fma_f32 v82, -v25, v73, v82
	v_fma_f32 v82, -v26, v74, v82
	v_fma_f32 v82, -v27, v75, v82
	s_waitcnt lgkmcnt(5)
	v_fma_f32 v82, -v28, v76, v82
	v_fma_f32 v82, -v29, v77, v82
	v_fma_f32 v82, -v30, v78, v82
	v_fma_f32 v82, -v31, v79, v82
	s_waitcnt lgkmcnt(4)
	v_fma_f32 v82, -v32, v80, v82
	v_fma_f32 v82, -v33, v81, v82
	s_waitcnt lgkmcnt(3)
	v_fma_f32 v83, -v38, v68, v83
	v_fma_f32 v83, -v39, v69, v83
	v_fma_f32 v83, -v40, v70, v83
	v_fma_f32 v83, -v41, v71, v83
	s_waitcnt lgkmcnt(2)
	v_fma_f32 v83, -v42, v72, v83
	v_fma_f32 v83, -v43, v73, v83
	v_fma_f32 v83, -v44, v74, v83
	v_fma_f32 v83, -v45, v75, v83
	s_waitcnt lgkmcnt(1)
	v_fma_f32 v83, -v46, v76, v83
	v_fma_f32 v83, -v47, v77, v83
	v_fma_f32 v83, -v48, v78, v83
	v_fma_f32 v83, -v49, v79, v83
	s_waitcnt lgkmcnt(0)
	v_fma_f32 v83, -v50, v80, v83
	v_fma_f32 v83, -v51, v81, v83
	v_fma_f32 v83, -v52, v82, v83
	ds_write_b32 v58, v68 offset:16384
	ds_write_b32 v58, v69 offset:17408
	ds_write_b32 v58, v70 offset:18432
	ds_write_b32 v58, v71 offset:19456
	ds_write_b32 v58, v72 offset:20480
	ds_write_b32 v58, v73 offset:21504
	ds_write_b32 v58, v74 offset:22528
	ds_write_b32 v58, v75 offset:23552
	ds_write_b32 v58, v76 offset:24576
	ds_write_b32 v58, v77 offset:25600
	ds_write_b32 v58, v78 offset:26624
	ds_write_b32 v58, v79 offset:27648
	ds_write_b32 v58, v80 offset:28672
	ds_write_b32 v58, v81 offset:29696
	ds_write_b32 v58, v82 offset:30720
	ds_write_b32 v58, v83 offset:31744
	v_cvt_pk_bf16_f32 v2, v68, v69
	v_cvt_pk_bf16_f32 v3, v70, v71
	v_cvt_pk_bf16_f32 v4, v76, v77
	v_cvt_pk_bf16_f32 v5, v78, v79
	global_store_dwordx4 v60, v[2:5], s[36:37] offset:16
	v_cvt_pk_bf16_f32 v6, v72, v73
	v_cvt_pk_bf16_f32 v7, v74, v75
	v_cvt_pk_bf16_f32 v8, v80, v81
	v_cvt_pk_bf16_f32 v9, v82, v83
	global_store_dwordx4 v60, v[6:9], s[36:37] offset:1040
	ds_read_b32 v36, v54 offset:8704
	ds_read_b32 v38, v55 offset:0
	ds_read_b32 v39, v55 offset:64
	ds_read_b32 v40, v55 offset:128
	ds_read_b32 v41, v55 offset:192
	ds_read_b32 v19, v54 offset:8720
	ds_read_b32 v42, v55 offset:4096
	ds_read_b32 v43, v55 offset:4160
	ds_read_b32 v44, v55 offset:4224
	ds_read_b32 v45, v55 offset:4288
	s_waitcnt lgkmcnt(8)
	v_mfma_f32_16x16x4_f32 v[20:23], v36, v38, 0
	s_waitcnt lgkmcnt(7)
	v_mfma_f32_16x16x4_f32 v[24:27], v36, v39, 0
	s_waitcnt lgkmcnt(6)
	v_mfma_f32_16x16x4_f32 v[28:31], v36, v40, 0
	s_waitcnt lgkmcnt(5)
	v_mfma_f32_16x16x4_f32 v[32:35], v36, v41, 0
	ds_read_b32 v36, v54 offset:8736
	ds_read_b32 v38, v55 offset:8192
	ds_read_b32 v39, v55 offset:8256
	ds_read_b32 v40, v55 offset:8320
	ds_read_b32 v41, v55 offset:8384
	s_waitcnt lgkmcnt(8)
	v_mfma_f32_16x16x4_f32 v[20:23], v19, v42, v[20:23]
	s_waitcnt lgkmcnt(7)
	v_mfma_f32_16x16x4_f32 v[24:27], v19, v43, v[24:27]
	s_waitcnt lgkmcnt(6)
	v_mfma_f32_16x16x4_f32 v[28:31], v19, v44, v[28:31]
	s_waitcnt lgkmcnt(5)
	v_mfma_f32_16x16x4_f32 v[32:35], v19, v45, v[32:35]
	ds_read_b32 v19, v54 offset:8752
	ds_read_b32 v42, v55 offset:12288
	ds_read_b32 v43, v55 offset:12352
	ds_read_b32 v44, v55 offset:12416
	ds_read_b32 v45, v55 offset:12480
	s_waitcnt lgkmcnt(8)
	v_mfma_f32_16x16x4_f32 v[20:23], v36, v38, v[20:23]
	s_waitcnt lgkmcnt(7)
	v_mfma_f32_16x16x4_f32 v[24:27], v36, v39, v[24:27]
	s_waitcnt lgkmcnt(6)
	v_mfma_f32_16x16x4_f32 v[28:31], v36, v40, v[28:31]
	s_waitcnt lgkmcnt(5)
	v_mfma_f32_16x16x4_f32 v[32:35], v36, v41, v[32:35]
	ds_read_b32 v36, v54 offset:8768
	ds_read_b32 v38, v55 offset:16384
	ds_read_b32 v39, v55 offset:16448
	ds_read_b32 v40, v55 offset:16512
	ds_read_b32 v41, v55 offset:16576
	s_waitcnt lgkmcnt(8)
	v_mfma_f32_16x16x4_f32 v[20:23], v19, v42, v[20:23]
	s_waitcnt lgkmcnt(7)
	v_mfma_f32_16x16x4_f32 v[24:27], v19, v43, v[24:27]
	s_waitcnt lgkmcnt(6)
	v_mfma_f32_16x16x4_f32 v[28:31], v19, v44, v[28:31]
	s_waitcnt lgkmcnt(5)
	v_mfma_f32_16x16x4_f32 v[32:35], v19, v45, v[32:35]
	ds_read_b32 v19, v54 offset:8784
	ds_read_b32 v42, v55 offset:20480
	ds_read_b32 v43, v55 offset:20544
	ds_read_b32 v44, v55 offset:20608
	ds_read_b32 v45, v55 offset:20672
	s_waitcnt lgkmcnt(8)
	v_mfma_f32_16x16x4_f32 v[20:23], v36, v38, v[20:23]
	s_waitcnt lgkmcnt(7)
	v_mfma_f32_16x16x4_f32 v[24:27], v36, v39, v[24:27]
	s_waitcnt lgkmcnt(6)
; #define LAS __attribute__((address_space(3)))
; __device__ __forceinline__ float bf2f(bf16_t h) { return __uint_as_float(((unsigned)h) << 16); }
; __device__ __forceinline__ bf16_t f2bf(float f) { return (bf16_t)(cvt_pk(f, 0.f) & 0xffffu); }
; __device__ __forceinline__ void gdn_intra_item(const Ctx& a, int l, int h, int c, LAS unsigned char* lds) {
;     ...
;     if (tid < 256) {
;         const int cc = tid, d = cc & 127;
;         LAS float* xc = vf + cc;
;         bf16_t* dst = (bf16_t*)(a.ws + B_GW) + (size_t)t0 * 512 + h * 128 + d;
;         bf16_t* dstu = (bf16_t*)(a.ws + B_GU) + ((size_t)((h * 128 + c) * 4 + (d >> 5)) * 2) * 1024 + (d & 31) * 16;
; #pragma unroll 1
;         for (int bs = 0; bs < 64; bs += 16) {
;             float acc[16];
;             if (cc < 128) {
; #pragma unroll
;                 for (int r = 0; r < 16; ++r) { const int i = bs + r; acc[r] = xc[i * 256] * be[i]; }
;             } else {
; #pragma unroll
;                 for (int r = 0; r < 16; ++r) { const int i = bs + r; acc[r] = bf2f(kb[i * 136 + d]) * rkv[i] * be[i] * eg[i]; }
;             }
; #pragma unroll 1
;             for (int j = 0; j < bs; j += 4) {
;                 const float x0 = xc[(j + 0) * 256], x1 = xc[(j + 1) * 256], x2 = xc[(j + 2) * 256], x3 = xc[(j + 3) * 256];
; #pragma unroll
;                 for (int r = 0; r < 16; ++r) {
;                     f32x4 av = *(const LAS f32x4*)(Am + (bs + r) * 68 + j);
;                     acc[r] -= av[0] * x0 + av[1] * x1 + av[2] * x2 + av[3] * x3;
;                 }
;             }
; #pragma unroll
;             for (int r = 0; r < 16; ++r) {
; #pragma unroll
;                 for (int c4 = 0; c4 < (r + 3) / 4; ++c4) {
;                     f32x4 av = *(const LAS f32x4*)(Am + (bs + r) * 68 + bs + c4 * 4);
; #pragma unroll
;                     for (int e = 0; e < 4; ++e) if (c4 * 4 + e < r) acc[r] -= av[e] * acc[c4 * 4 + e];
;                 }
;                 const int i = bs + r;
;                 xc[i * 256] = acc[r];
;                 { const int i32 = i & 31; const int offu = (i >> 5) * 1024 + ((i32 >> 2) & 1) * 512 + (i32 >> 3) * 4 + (i & 3);
;                   bf16_t* ob = (cc < 128) ? dstu : dst; ob[(cc < 128) ? offu : i * 512] = f2bf(acc[r]); }
;             }
;         }
	v_mfma_f32_16x16x4_f32 v[28:31], v36, v40, v[28:31]
	s_waitcnt lgkmcnt(5)
	v_mfma_f32_16x16x4_f32 v[32:35], v36, v41, v[32:35]
	ds_read_b32 v36, v54 offset:8800
	ds_read_b32 v38, v55 offset:24576
	ds_read_b32 v39, v55 offset:24640
	ds_read_b32 v40, v55 offset:24704
	ds_read_b32 v41, v55 offset:24768
	s_waitcnt lgkmcnt(8)
	v_mfma_f32_16x16x4_f32 v[20:23], v19, v42, v[20:23]
	s_waitcnt lgkmcnt(7)
	v_mfma_f32_16x16x4_f32 v[24:27], v19, v43, v[24:27]
	s_waitcnt lgkmcnt(6)
	v_mfma_f32_16x16x4_f32 v[28:31], v19, v44, v[28:31]
	s_waitcnt lgkmcnt(5)
	v_mfma_f32_16x16x4_f32 v[32:35], v19, v45, v[32:35]
	ds_read_b32 v19, v54 offset:8816
	ds_read_b32 v42, v55 offset:28672
	ds_read_b32 v43, v55 offset:28736
	ds_read_b32 v44, v55 offset:28800
	ds_read_b32 v45, v55 offset:28864
	s_waitcnt lgkmcnt(8)
	v_mfma_f32_16x16x4_f32 v[20:23], v36, v38, v[20:23]
	s_waitcnt lgkmcnt(7)
	v_mfma_f32_16x16x4_f32 v[24:27], v36, v39, v[24:27]
	s_waitcnt lgkmcnt(6)
	v_mfma_f32_16x16x4_f32 v[28:31], v36, v40, v[28:31]
	s_waitcnt lgkmcnt(5)
	v_mfma_f32_16x16x4_f32 v[32:35], v36, v41, v[32:35]
	s_waitcnt lgkmcnt(3)
	v_mfma_f32_16x16x4_f32 v[20:23], v19, v42, v[20:23]
	s_waitcnt lgkmcnt(2)
	v_mfma_f32_16x16x4_f32 v[24:27], v19, v43, v[24:27]
	s_waitcnt lgkmcnt(1)
	v_mfma_f32_16x16x4_f32 v[28:31], v19, v44, v[28:31]
	s_waitcnt lgkmcnt(0)
	v_mfma_f32_16x16x4_f32 v[32:35], v19, v45, v[32:35]
	s_nop 5
	ds_write_b128 v56, v[20:23] offset:0
	s_nop 0
	ds_write_b128 v56, v[24:27] offset:1280
	s_nop 0
	ds_write_b128 v56, v[28:31] offset:2560
	s_nop 0
	ds_write_b128 v56, v[32:35] offset:3840
	ds_read_b128 v[2:5], v57 offset:0
	ds_read_b128 v[6:9], v57 offset:16
	ds_read_b128 v[10:13], v57 offset:32
	ds_read_b128 v[14:17], v57 offset:48
	ds_read_b128 v[38:41], v62 offset:17792
	ds_read_b128 v[42:45], v62 offset:17808
	ds_read_b128 v[46:49], v62 offset:17824
	ds_read_b128 v[50:53], v62 offset:17840
	ds_read_b32 v68, v58 offset:32768
	ds_read_b32 v69, v58 offset:33792
	ds_read_b32 v70, v58 offset:34816
	ds_read_b32 v71, v58 offset:35840
	ds_read_b32 v72, v58 offset:36864
	ds_read_b32 v73, v58 offset:37888
	ds_read_b32 v74, v58 offset:38912
	ds_read_b32 v75, v58 offset:39936
	ds_read_b32 v76, v58 offset:40960
	ds_read_b32 v77, v58 offset:41984
	ds_read_b32 v78, v58 offset:43008
	ds_read_b32 v79, v58 offset:44032
	ds_read_b32 v80, v58 offset:45056
	ds_read_b32 v81, v58 offset:46080
	ds_read_b32 v82, v58 offset:47104
	ds_read_b32 v83, v58 offset:48128
	s_waitcnt lgkmcnt(15)
	v_fma_f32 v68, v68, v38, -v2
	s_waitcnt lgkmcnt(14)
	v_fma_f32 v69, v69, v39, -v3
	s_waitcnt lgkmcnt(13)
	v_fma_f32 v70, v70, v40, -v4
	s_waitcnt lgkmcnt(12)
	v_fma_f32 v71, v71, v41, -v5
	s_waitcnt lgkmcnt(11)
	v_fma_f32 v72, v72, v42, -v6
	s_waitcnt lgkmcnt(10)
	v_fma_f32 v73, v73, v43, -v7
	s_waitcnt lgkmcnt(9)
	v_fma_f32 v74, v74, v44, -v8
	s_waitcnt lgkmcnt(8)
	v_fma_f32 v75, v75, v45, -v9
	s_waitcnt lgkmcnt(7)
	v_fma_f32 v76, v76, v46, -v10
	s_waitcnt lgkmcnt(6)
	v_fma_f32 v77, v77, v47, -v11
	s_waitcnt lgkmcnt(5)
	v_fma_f32 v78, v78, v48, -v12
	s_waitcnt lgkmcnt(4)
	v_fma_f32 v79, v79, v49, -v13
	s_waitcnt lgkmcnt(3)
	v_fma_f32 v80, v80, v50, -v14
	s_waitcnt lgkmcnt(2)
	v_fma_f32 v81, v81, v51, -v15
	s_waitcnt lgkmcnt(1)
	v_fma_f32 v82, v82, v52, -v16
	s_waitcnt lgkmcnt(0)
	v_fma_f32 v83, v83, v53, -v17
	ds_read_b128 v[38:41], v62 offset:9104
	ds_read_b128 v[20:23], v62 offset:9376
	s_waitcnt lgkmcnt(1)
	v_fma_f32 v69, -v38, v68, v69
	ds_read_b128 v[38:41], v62 offset:9648
	s_waitcnt lgkmcnt(1)
	v_fma_f32 v70, -v20, v68, v70
	v_fma_f32 v70, -v21, v69, v70
	ds_read_b128 v[20:23], v62 offset:9920
	s_waitcnt lgkmcnt(1)
	v_fma_f32 v71, -v38, v68, v71
	v_fma_f32 v71, -v39, v69, v71
	v_fma_f32 v71, -v40, v70, v71
	ds_read_b128 v[38:41], v62 offset:10192
	ds_read_b128 v[42:45], v62 offset:10208
	s_waitcnt lgkmcnt(2)
	v_fma_f32 v72, -v20, v68, v72
	v_fma_f32 v72, -v21, v69, v72
	v_fma_f32 v72, -v22, v70, v72
	v_fma_f32 v72, -v23, v71, v72
	ds_read_b128 v[20:23], v62 offset:10464
	ds_read_b128 v[24:27], v62 offset:10480
	s_waitcnt lgkmcnt(3)
	v_fma_f32 v73, -v38, v68, v73
	v_fma_f32 v73, -v39, v69, v73
	v_fma_f32 v73, -v40, v70, v73
	v_fma_f32 v73, -v41, v71, v73
	s_waitcnt lgkmcnt(2)
	v_fma_f32 v73, -v42, v72, v73
	ds_read_b128 v[38:41], v62 offset:10736
	ds_read_b128 v[42:45], v62 offset:10752
	s_waitcnt lgkmcnt(3)
	v_fma_f32 v74, -v20, v68, v74
	v_fma_f32 v74, -v21, v69, v74
	v_fma_f32 v74, -v22, v70, v74
	v_fma_f32 v74, -v23, v71, v74
	s_waitcnt lgkmcnt(2)
	v_fma_f32 v74, -v24, v72, v74
	v_fma_f32 v74, -v25, v73, v74
	ds_read_b128 v[20:23], v62 offset:11008
	ds_read_b128 v[24:27], v62 offset:11024
	s_waitcnt lgkmcnt(3)
	v_fma_f32 v75, -v38, v68, v75
	v_fma_f32 v75, -v39, v69, v75
	v_fma_f32 v75, -v40, v70, v75
	v_fma_f32 v75, -v41, v71, v75
	s_waitcnt lgkmcnt(2)
	v_fma_f32 v75, -v42, v72, v75
	v_fma_f32 v75, -v43, v73, v75
	v_fma_f32 v75, -v44, v74, v75
	ds_read_b128 v[38:41], v62 offset:11280
	ds_read_b128 v[42:45], v62 offset:11296
	ds_read_b128 v[46:49], v62 offset:11312
	s_waitcnt lgkmcnt(4)
	v_fma_f32 v76, -v20, v68, v76
	v_fma_f32 v76, -v21, v69, v76
	v_fma_f32 v76, -v22, v70, v76
	v_fma_f32 v76, -v23, v71, v76
	s_waitcnt lgkmcnt(3)
	v_fma_f32 v76, -v24, v72, v76
	v_fma_f32 v76, -v25, v73, v76
	v_fma_f32 v76, -v26, v74, v76
	v_fma_f32 v76, -v27, v75, v76
	ds_read_b128 v[20:23], v62 offset:11552
	ds_read_b128 v[24:27], v62 offset:11568
	ds_read_b128 v[28:31], v62 offset:11584
	s_waitcnt lgkmcnt(5)
	v_fma_f32 v77, -v38, v68, v77
	v_fma_f32 v77, -v39, v69, v77
	v_fma_f32 v77, -v40, v70, v77
	v_fma_f32 v77, -v41, v71, v77
	s_waitcnt lgkmcnt(4)
; #define LAS __attribute__((address_space(3)))
; __device__ __forceinline__ float bf2f(bf16_t h) { return __uint_as_float(((unsigned)h) << 16); }
; __device__ __forceinline__ bf16_t f2bf(float f) { return (bf16_t)(cvt_pk(f, 0.f) & 0xffffu); }
; __device__ __forceinline__ void gdn_intra_item(const Ctx& a, int l, int h, int c, LAS unsigned char* lds) {
;     ...
;     if (tid < 256) {
;         const int cc = tid, d = cc & 127;
;         LAS float* xc = vf + cc;
;         bf16_t* dst = (bf16_t*)(a.ws + B_GW) + (size_t)t0 * 512 + h * 128 + d;
;         bf16_t* dstu = (bf16_t*)(a.ws + B_GU) + ((size_t)((h * 128 + c) * 4 + (d >> 5)) * 2) * 1024 + (d & 31) * 16;
; #pragma unroll 1
;         for (int bs = 0; bs < 64; bs += 16) {
;             float acc[16];
;             if (cc < 128) {
; #pragma unroll
;                 for (int r = 0; r < 16; ++r) { const int i = bs + r; acc[r] = xc[i * 256] * be[i]; }
;             } else {
; #pragma unroll
;                 for (int r = 0; r < 16; ++r) { const int i = bs + r; acc[r] = bf2f(kb[i * 136 + d]) * rkv[i] * be[i] * eg[i]; }
;             }
; #pragma unroll 1
;             for (int j = 0; j < bs; j += 4) {
;                 const float x0 = xc[(j + 0) * 256], x1 = xc[(j + 1) * 256], x2 = xc[(j + 2) * 256], x3 = xc[(j + 3) * 256];
; #pragma unroll
;                 for (int r = 0; r < 16; ++r) {
;                     f32x4 av = *(const LAS f32x4*)(Am + (bs + r) * 68 + j);
;                     acc[r] -= av[0] * x0 + av[1] * x1 + av[2] * x2 + av[3] * x3;
;                 }
;             }
; #pragma unroll
;             for (int r = 0; r < 16; ++r) {
; #pragma unroll
;                 for (int c4 = 0; c4 < (r + 3) / 4; ++c4) {
;                     f32x4 av = *(const LAS f32x4*)(Am + (bs + r) * 68 + bs + c4 * 4);
; #pragma unroll
;                     for (int e = 0; e < 4; ++e) if (c4 * 4 + e < r) acc[r] -= av[e] * acc[c4 * 4 + e];
;                 }
;                 const int i = bs + r;
;                 xc[i * 256] = acc[r];
;                 { const int i32 = i & 31; const int offu = (i >> 5) * 1024 + ((i32 >> 2) & 1) * 512 + (i32 >> 3) * 4 + (i & 3);
;                   bf16_t* ob = (cc < 128) ? dstu : dst; ob[(cc < 128) ? offu : i * 512] = f2bf(acc[r]); }
;             }
;         }
	v_fma_f32 v77, -v42, v72, v77
	v_fma_f32 v77, -v43, v73, v77
	v_fma_f32 v77, -v44, v74, v77
	v_fma_f32 v77, -v45, v75, v77
	s_waitcnt lgkmcnt(3)
	v_fma_f32 v77, -v46, v76, v77
	ds_read_b128 v[38:41], v62 offset:11824
	ds_read_b128 v[42:45], v62 offset:11840
	ds_read_b128 v[46:49], v62 offset:11856
	s_waitcnt lgkmcnt(5)
	v_fma_f32 v78, -v20, v68, v78
	v_fma_f32 v78, -v21, v69, v78
	v_fma_f32 v78, -v22, v70, v78
	v_fma_f32 v78, -v23, v71, v78
	s_waitcnt lgkmcnt(4)
	v_fma_f32 v78, -v24, v72, v78
	v_fma_f32 v78, -v25, v73, v78
	v_fma_f32 v78, -v26, v74, v78
	v_fma_f32 v78, -v27, v75, v78
	s_waitcnt lgkmcnt(3)
	v_fma_f32 v78, -v28, v76, v78
	v_fma_f32 v78, -v29, v77, v78
	ds_read_b128 v[20:23], v62 offset:12096
	ds_read_b128 v[24:27], v62 offset:12112
	ds_read_b128 v[28:31], v62 offset:12128
	s_waitcnt lgkmcnt(5)
	v_fma_f32 v79, -v38, v68, v79
	v_fma_f32 v79, -v39, v69, v79
	v_fma_f32 v79, -v40, v70, v79
	v_fma_f32 v79, -v41, v71, v79
	s_waitcnt lgkmcnt(4)
	v_fma_f32 v79, -v42, v72, v79
	v_fma_f32 v79, -v43, v73, v79
	v_fma_f32 v79, -v44, v74, v79
	v_fma_f32 v79, -v45, v75, v79
	s_waitcnt lgkmcnt(3)
	v_fma_f32 v79, -v46, v76, v79
	v_fma_f32 v79, -v47, v77, v79
	v_fma_f32 v79, -v48, v78, v79
	ds_read_b128 v[38:41], v62 offset:12368
	ds_read_b128 v[42:45], v62 offset:12384
	ds_read_b128 v[46:49], v62 offset:12400
	ds_read_b128 v[50:53], v62 offset:12416
	s_waitcnt lgkmcnt(6)
	v_fma_f32 v80, -v20, v68, v80
	v_fma_f32 v80, -v21, v69, v80
	v_fma_f32 v80, -v22, v70, v80
	v_fma_f32 v80, -v23, v71, v80
	s_waitcnt lgkmcnt(5)
	v_fma_f32 v80, -v24, v72, v80
	v_fma_f32 v80, -v25, v73, v80
	v_fma_f32 v80, -v26, v74, v80
	v_fma_f32 v80, -v27, v75, v80
	s_waitcnt lgkmcnt(4)
	v_fma_f32 v80, -v28, v76, v80
	v_fma_f32 v80, -v29, v77, v80
	v_fma_f32 v80, -v30, v78, v80
	v_fma_f32 v80, -v31, v79, v80
	ds_read_b128 v[20:23], v62 offset:12640
	ds_read_b128 v[24:27], v62 offset:12656
	ds_read_b128 v[28:31], v62 offset:12672
	ds_read_b128 v[32:35], v62 offset:12688
	s_waitcnt lgkmcnt(7)
	v_fma_f32 v81, -v38, v68, v81
	v_fma_f32 v81, -v39, v69, v81
	v_fma_f32 v81, -v40, v70, v81
	v_fma_f32 v81, -v41, v71, v81
	s_waitcnt lgkmcnt(6)
	v_fma_f32 v81, -v42, v72, v81
	v_fma_f32 v81, -v43, v73, v81
	v_fma_f32 v81, -v44, v74, v81
	v_fma_f32 v81, -v45, v75, v81
	s_waitcnt lgkmcnt(5)
	v_fma_f32 v81, -v46, v76, v81
	v_fma_f32 v81, -v47, v77, v81
	v_fma_f32 v81, -v48, v78, v81
	v_fma_f32 v81, -v49, v79, v81
	s_waitcnt lgkmcnt(4)
	v_fma_f32 v81, -v50, v80, v81
	ds_read_b128 v[38:41], v62 offset:12912
	ds_read_b128 v[42:45], v62 offset:12928
	ds_read_b128 v[46:49], v62 offset:12944
	ds_read_b128 v[50:53], v62 offset:12960
	s_waitcnt lgkmcnt(7)
	v_fma_f32 v82, -v20, v68, v82
	v_fma_f32 v82, -v21, v69, v82
	v_fma_f32 v82, -v22, v70, v82
	v_fma_f32 v82, -v23, v71, v82
	s_waitcnt lgkmcnt(6)
	v_fma_f32 v82, -v24, v72, v82
	v_fma_f32 v82, -v25, v73, v82
	v_fma_f32 v82, -v26, v74, v82
	v_fma_f32 v82, -v27, v75, v82
	s_waitcnt lgkmcnt(5)
	v_fma_f32 v82, -v28, v76, v82
	v_fma_f32 v82, -v29, v77, v82
	v_fma_f32 v82, -v30, v78, v82
	v_fma_f32 v82, -v31, v79, v82
	s_waitcnt lgkmcnt(4)
	v_fma_f32 v82, -v32, v80, v82
	v_fma_f32 v82, -v33, v81, v82
	s_waitcnt lgkmcnt(3)
	v_fma_f32 v83, -v38, v68, v83
	v_fma_f32 v83, -v39, v69, v83
	v_fma_f32 v83, -v40, v70, v83
	v_fma_f32 v83, -v41, v71, v83
	s_waitcnt lgkmcnt(2)
	v_fma_f32 v83, -v42, v72, v83
	v_fma_f32 v83, -v43, v73, v83
	v_fma_f32 v83, -v44, v74, v83
	v_fma_f32 v83, -v45, v75, v83
	s_waitcnt lgkmcnt(1)
	v_fma_f32 v83, -v46, v76, v83
	v_fma_f32 v83, -v47, v77, v83
	v_fma_f32 v83, -v48, v78, v83
	v_fma_f32 v83, -v49, v79, v83
	s_waitcnt lgkmcnt(0)
	v_fma_f32 v83, -v50, v80, v83
	v_fma_f32 v83, -v51, v81, v83
	v_fma_f32 v83, -v52, v82, v83
	ds_write_b32 v58, v68 offset:32768
	ds_write_b32 v58, v69 offset:33792
	ds_write_b32 v58, v70 offset:34816
	ds_write_b32 v58, v71 offset:35840
	ds_write_b32 v58, v72 offset:36864
	ds_write_b32 v58, v73 offset:37888
	ds_write_b32 v58, v74 offset:38912
	ds_write_b32 v58, v75 offset:39936
	ds_write_b32 v58, v76 offset:40960
	ds_write_b32 v58, v77 offset:41984
	ds_write_b32 v58, v78 offset:43008
	ds_write_b32 v58, v79 offset:44032
	ds_write_b32 v58, v80 offset:45056
	ds_write_b32 v58, v81 offset:46080
	ds_write_b32 v58, v82 offset:47104
	ds_write_b32 v58, v83 offset:48128
	v_cvt_pk_bf16_f32 v2, v68, v69
	v_cvt_pk_bf16_f32 v3, v70, v71
	v_cvt_pk_bf16_f32 v4, v76, v77
	v_cvt_pk_bf16_f32 v5, v78, v79
	global_store_dwordx4 v60, v[2:5], s[36:37] offset:2048
	v_cvt_pk_bf16_f32 v6, v72, v73
	v_cvt_pk_bf16_f32 v7, v74, v75
	v_cvt_pk_bf16_f32 v8, v80, v81
	v_cvt_pk_bf16_f32 v9, v82, v83
	global_store_dwordx4 v60, v[6:9], s[36:37] offset:3072
	ds_read_b32 v36, v54 offset:13056
	ds_read_b32 v38, v55 offset:0
	ds_read_b32 v39, v55 offset:64
	ds_read_b32 v40, v55 offset:128
	ds_read_b32 v41, v55 offset:192
	ds_read_b32 v19, v54 offset:13072
	ds_read_b32 v42, v55 offset:4096
	ds_read_b32 v43, v55 offset:4160
	ds_read_b32 v44, v55 offset:4224
	ds_read_b32 v45, v55 offset:4288
	s_waitcnt lgkmcnt(8)
	v_mfma_f32_16x16x4_f32 v[20:23], v36, v38, 0
	s_waitcnt lgkmcnt(7)
	v_mfma_f32_16x16x4_f32 v[24:27], v36, v39, 0
	s_waitcnt lgkmcnt(6)
	v_mfma_f32_16x16x4_f32 v[28:31], v36, v40, 0
	s_waitcnt lgkmcnt(5)
	v_mfma_f32_16x16x4_f32 v[32:35], v36, v41, 0
	ds_read_b32 v36, v54 offset:13088
	ds_read_b32 v38, v55 offset:8192
	ds_read_b32 v39, v55 offset:8256
	ds_read_b32 v40, v55 offset:8320
	ds_read_b32 v41, v55 offset:8384
	s_waitcnt lgkmcnt(8)
	v_mfma_f32_16x16x4_f32 v[20:23], v19, v42, v[20:23]
	s_waitcnt lgkmcnt(7)
	v_mfma_f32_16x16x4_f32 v[24:27], v19, v43, v[24:27]
	s_waitcnt lgkmcnt(6)
	v_mfma_f32_16x16x4_f32 v[28:31], v19, v44, v[28:31]
	s_waitcnt lgkmcnt(5)
; #define LAS __attribute__((address_space(3)))
; __device__ __forceinline__ float bf2f(bf16_t h) { return __uint_as_float(((unsigned)h) << 16); }
; __device__ __forceinline__ bf16_t f2bf(float f) { return (bf16_t)(cvt_pk(f, 0.f) & 0xffffu); }
; __device__ __forceinline__ void gdn_intra_item(const Ctx& a, int l, int h, int c, LAS unsigned char* lds) {
;     ...
;     if (tid < 256) {
;         const int cc = tid, d = cc & 127;
;         LAS float* xc = vf + cc;
;         bf16_t* dst = (bf16_t*)(a.ws + B_GW) + (size_t)t0 * 512 + h * 128 + d;
;         bf16_t* dstu = (bf16_t*)(a.ws + B_GU) + ((size_t)((h * 128 + c) * 4 + (d >> 5)) * 2) * 1024 + (d & 31) * 16;
; #pragma unroll 1
;         for (int bs = 0; bs < 64; bs += 16) {
;             float acc[16];
;             if (cc < 128) {
; #pragma unroll
;                 for (int r = 0; r < 16; ++r) { const int i = bs + r; acc[r] = xc[i * 256] * be[i]; }
;             } else {
; #pragma unroll
;                 for (int r = 0; r < 16; ++r) { const int i = bs + r; acc[r] = bf2f(kb[i * 136 + d]) * rkv[i] * be[i] * eg[i]; }
;             }
; #pragma unroll 1
;             for (int j = 0; j < bs; j += 4) {
;                 const float x0 = xc[(j + 0) * 256], x1 = xc[(j + 1) * 256], x2 = xc[(j + 2) * 256], x3 = xc[(j + 3) * 256];
; #pragma unroll
;                 for (int r = 0; r < 16; ++r) {
;                     f32x4 av = *(const LAS f32x4*)(Am + (bs + r) * 68 + j);
;                     acc[r] -= av[0] * x0 + av[1] * x1 + av[2] * x2 + av[3] * x3;
;                 }
;             }
; #pragma unroll
;             for (int r = 0; r < 16; ++r) {
; #pragma unroll
;                 for (int c4 = 0; c4 < (r + 3) / 4; ++c4) {
;                     f32x4 av = *(const LAS f32x4*)(Am + (bs + r) * 68 + bs + c4 * 4);
; #pragma unroll
;                     for (int e = 0; e < 4; ++e) if (c4 * 4 + e < r) acc[r] -= av[e] * acc[c4 * 4 + e];
;                 }
;                 const int i = bs + r;
;                 xc[i * 256] = acc[r];
;                 { const int i32 = i & 31; const int offu = (i >> 5) * 1024 + ((i32 >> 2) & 1) * 512 + (i32 >> 3) * 4 + (i & 3);
;                   bf16_t* ob = (cc < 128) ? dstu : dst; ob[(cc < 128) ? offu : i * 512] = f2bf(acc[r]); }
;             }
;         }
	v_mfma_f32_16x16x4_f32 v[32:35], v19, v45, v[32:35]
	ds_read_b32 v19, v54 offset:13104
	ds_read_b32 v42, v55 offset:12288
	ds_read_b32 v43, v55 offset:12352
	ds_read_b32 v44, v55 offset:12416
	ds_read_b32 v45, v55 offset:12480
	s_waitcnt lgkmcnt(8)
	v_mfma_f32_16x16x4_f32 v[20:23], v36, v38, v[20:23]
	s_waitcnt lgkmcnt(7)
	v_mfma_f32_16x16x4_f32 v[24:27], v36, v39, v[24:27]
	s_waitcnt lgkmcnt(6)
	v_mfma_f32_16x16x4_f32 v[28:31], v36, v40, v[28:31]
	s_waitcnt lgkmcnt(5)
	v_mfma_f32_16x16x4_f32 v[32:35], v36, v41, v[32:35]
	ds_read_b32 v36, v54 offset:13120
	ds_read_b32 v38, v55 offset:16384
	ds_read_b32 v39, v55 offset:16448
	ds_read_b32 v40, v55 offset:16512
	ds_read_b32 v41, v55 offset:16576
	s_waitcnt lgkmcnt(8)
	v_mfma_f32_16x16x4_f32 v[20:23], v19, v42, v[20:23]
	s_waitcnt lgkmcnt(7)
	v_mfma_f32_16x16x4_f32 v[24:27], v19, v43, v[24:27]
	s_waitcnt lgkmcnt(6)
	v_mfma_f32_16x16x4_f32 v[28:31], v19, v44, v[28:31]
	s_waitcnt lgkmcnt(5)
	v_mfma_f32_16x16x4_f32 v[32:35], v19, v45, v[32:35]
	ds_read_b32 v19, v54 offset:13136
	ds_read_b32 v42, v55 offset:20480
	ds_read_b32 v43, v55 offset:20544
	ds_read_b32 v44, v55 offset:20608
	ds_read_b32 v45, v55 offset:20672
	s_waitcnt lgkmcnt(8)
	v_mfma_f32_16x16x4_f32 v[20:23], v36, v38, v[20:23]
	s_waitcnt lgkmcnt(7)
	v_mfma_f32_16x16x4_f32 v[24:27], v36, v39, v[24:27]
	s_waitcnt lgkmcnt(6)
	v_mfma_f32_16x16x4_f32 v[28:31], v36, v40, v[28:31]
	s_waitcnt lgkmcnt(5)
	v_mfma_f32_16x16x4_f32 v[32:35], v36, v41, v[32:35]
	ds_read_b32 v36, v54 offset:13152
	ds_read_b32 v38, v55 offset:24576
	ds_read_b32 v39, v55 offset:24640
	ds_read_b32 v40, v55 offset:24704
	ds_read_b32 v41, v55 offset:24768
	s_waitcnt lgkmcnt(8)
	v_mfma_f32_16x16x4_f32 v[20:23], v19, v42, v[20:23]
	s_waitcnt lgkmcnt(7)
	v_mfma_f32_16x16x4_f32 v[24:27], v19, v43, v[24:27]
	s_waitcnt lgkmcnt(6)
	v_mfma_f32_16x16x4_f32 v[28:31], v19, v44, v[28:31]
	s_waitcnt lgkmcnt(5)
	v_mfma_f32_16x16x4_f32 v[32:35], v19, v45, v[32:35]
	ds_read_b32 v19, v54 offset:13168
	ds_read_b32 v42, v55 offset:28672
	ds_read_b32 v43, v55 offset:28736
	ds_read_b32 v44, v55 offset:28800
	ds_read_b32 v45, v55 offset:28864
	s_waitcnt lgkmcnt(8)
	v_mfma_f32_16x16x4_f32 v[20:23], v36, v38, v[20:23]
	s_waitcnt lgkmcnt(7)
	v_mfma_f32_16x16x4_f32 v[24:27], v36, v39, v[24:27]
	s_waitcnt lgkmcnt(6)
	v_mfma_f32_16x16x4_f32 v[28:31], v36, v40, v[28:31]
	s_waitcnt lgkmcnt(5)
	v_mfma_f32_16x16x4_f32 v[32:35], v36, v41, v[32:35]
	ds_read_b32 v36, v54 offset:13184
	ds_read_b32 v38, v55 offset:32768
	ds_read_b32 v39, v55 offset:32832
	ds_read_b32 v40, v55 offset:32896
	ds_read_b32 v41, v55 offset:32960
	s_waitcnt lgkmcnt(8)
	v_mfma_f32_16x16x4_f32 v[20:23], v19, v42, v[20:23]
	s_waitcnt lgkmcnt(7)
	v_mfma_f32_16x16x4_f32 v[24:27], v19, v43, v[24:27]
	s_waitcnt lgkmcnt(6)
	v_mfma_f32_16x16x4_f32 v[28:31], v19, v44, v[28:31]
	s_waitcnt lgkmcnt(5)
	v_mfma_f32_16x16x4_f32 v[32:35], v19, v45, v[32:35]
	ds_read_b32 v19, v54 offset:13200
	ds_read_b32 v42, v55 offset:36864
	ds_read_b32 v43, v55 offset:36928
	ds_read_b32 v44, v55 offset:36992
	ds_read_b32 v45, v55 offset:37056
	s_waitcnt lgkmcnt(8)
	v_mfma_f32_16x16x4_f32 v[20:23], v36, v38, v[20:23]
	s_waitcnt lgkmcnt(7)
	v_mfma_f32_16x16x4_f32 v[24:27], v36, v39, v[24:27]
	s_waitcnt lgkmcnt(6)
	v_mfma_f32_16x16x4_f32 v[28:31], v36, v40, v[28:31]
	s_waitcnt lgkmcnt(5)
	v_mfma_f32_16x16x4_f32 v[32:35], v36, v41, v[32:35]
	ds_read_b32 v36, v54 offset:13216
	ds_read_b32 v38, v55 offset:40960
	ds_read_b32 v39, v55 offset:41024
	ds_read_b32 v40, v55 offset:41088
	ds_read_b32 v41, v55 offset:41152
	s_waitcnt lgkmcnt(8)
	v_mfma_f32_16x16x4_f32 v[20:23], v19, v42, v[20:23]
	s_waitcnt lgkmcnt(7)
	v_mfma_f32_16x16x4_f32 v[24:27], v19, v43, v[24:27]
	s_waitcnt lgkmcnt(6)
	v_mfma_f32_16x16x4_f32 v[28:31], v19, v44, v[28:31]
	s_waitcnt lgkmcnt(5)
	v_mfma_f32_16x16x4_f32 v[32:35], v19, v45, v[32:35]
	ds_read_b32 v19, v54 offset:13232
	ds_read_b32 v42, v55 offset:45056
	ds_read_b32 v43, v55 offset:45120
	ds_read_b32 v44, v55 offset:45184
	ds_read_b32 v45, v55 offset:45248
	s_waitcnt lgkmcnt(8)
	v_mfma_f32_16x16x4_f32 v[20:23], v36, v38, v[20:23]
	s_waitcnt lgkmcnt(7)
	v_mfma_f32_16x16x4_f32 v[24:27], v36, v39, v[24:27]
	s_waitcnt lgkmcnt(6)
	v_mfma_f32_16x16x4_f32 v[28:31], v36, v40, v[28:31]
	s_waitcnt lgkmcnt(5)
	v_mfma_f32_16x16x4_f32 v[32:35], v36, v41, v[32:35]
	s_waitcnt lgkmcnt(3)
	v_mfma_f32_16x16x4_f32 v[20:23], v19, v42, v[20:23]
	s_waitcnt lgkmcnt(2)
	v_mfma_f32_16x16x4_f32 v[24:27], v19, v43, v[24:27]
	s_waitcnt lgkmcnt(1)
	v_mfma_f32_16x16x4_f32 v[28:31], v19, v44, v[28:31]
	s_waitcnt lgkmcnt(0)
	v_mfma_f32_16x16x4_f32 v[32:35], v19, v45, v[32:35]
	s_nop 5
	ds_write_b128 v56, v[20:23] offset:0
	s_nop 0
	ds_write_b128 v56, v[24:27] offset:1280
	s_nop 0
	ds_write_b128 v56, v[28:31] offset:2560
	s_nop 0
	ds_write_b128 v56, v[32:35] offset:3840
	ds_read_b128 v[2:5], v57 offset:0
	ds_read_b128 v[6:9], v57 offset:16
	ds_read_b128 v[10:13], v57 offset:32
	ds_read_b128 v[14:17], v57 offset:48
	ds_read_b128 v[38:41], v62 offset:17856
	ds_read_b128 v[42:45], v62 offset:17872
	ds_read_b128 v[46:49], v62 offset:17888
	ds_read_b128 v[50:53], v62 offset:17904
	ds_read_b32 v68, v58 offset:49152
	ds_read_b32 v69, v58 offset:50176
	ds_read_b32 v70, v58 offset:51200
	ds_read_b32 v71, v58 offset:52224
	ds_read_b32 v72, v58 offset:53248
	ds_read_b32 v73, v58 offset:54272
	ds_read_b32 v74, v58 offset:55296
	ds_read_b32 v75, v58 offset:56320
	ds_read_b32 v76, v58 offset:57344
	ds_read_b32 v77, v58 offset:58368
	ds_read_b32 v78, v58 offset:59392
	ds_read_b32 v79, v58 offset:60416
	ds_read_b32 v80, v58 offset:61440
	ds_read_b32 v81, v58 offset:62464
	ds_read_b32 v82, v58 offset:63488
	ds_read_b32 v83, v58 offset:64512
	s_waitcnt lgkmcnt(15)
; #define LAS __attribute__((address_space(3)))
; __device__ __forceinline__ float bf2f(bf16_t h) { return __uint_as_float(((unsigned)h) << 16); }
; __device__ __forceinline__ bf16_t f2bf(float f) { return (bf16_t)(cvt_pk(f, 0.f) & 0xffffu); }
; __device__ __forceinline__ void gdn_intra_item(const Ctx& a, int l, int h, int c, LAS unsigned char* lds) {
;     ...
;     if (tid < 256) {
;         const int cc = tid, d = cc & 127;
;         LAS float* xc = vf + cc;
;         bf16_t* dst = (bf16_t*)(a.ws + B_GW) + (size_t)t0 * 512 + h * 128 + d;
;         bf16_t* dstu = (bf16_t*)(a.ws + B_GU) + ((size_t)((h * 128 + c) * 4 + (d >> 5)) * 2) * 1024 + (d & 31) * 16;
; #pragma unroll 1
;         for (int bs = 0; bs < 64; bs += 16) {
;             float acc[16];
;             if (cc < 128) {
; #pragma unroll
;                 for (int r = 0; r < 16; ++r) { const int i = bs + r; acc[r] = xc[i * 256] * be[i]; }
;             } else {
; #pragma unroll
;                 for (int r = 0; r < 16; ++r) { const int i = bs + r; acc[r] = bf2f(kb[i * 136 + d]) * rkv[i] * be[i] * eg[i]; }
;             }
; #pragma unroll 1
;             for (int j = 0; j < bs; j += 4) {
;                 const float x0 = xc[(j + 0) * 256], x1 = xc[(j + 1) * 256], x2 = xc[(j + 2) * 256], x3 = xc[(j + 3) * 256];
; #pragma unroll
;                 for (int r = 0; r < 16; ++r) {
;                     f32x4 av = *(const LAS f32x4*)(Am + (bs + r) * 68 + j);
;                     acc[r] -= av[0] * x0 + av[1] * x1 + av[2] * x2 + av[3] * x3;
;                 }
;             }
; #pragma unroll
;             for (int r = 0; r < 16; ++r) {
; #pragma unroll
;                 for (int c4 = 0; c4 < (r + 3) / 4; ++c4) {
;                     f32x4 av = *(const LAS f32x4*)(Am + (bs + r) * 68 + bs + c4 * 4);
; #pragma unroll
;                     for (int e = 0; e < 4; ++e) if (c4 * 4 + e < r) acc[r] -= av[e] * acc[c4 * 4 + e];
;                 }
;                 const int i = bs + r;
;                 xc[i * 256] = acc[r];
;                 { const int i32 = i & 31; const int offu = (i >> 5) * 1024 + ((i32 >> 2) & 1) * 512 + (i32 >> 3) * 4 + (i & 3);
;                   bf16_t* ob = (cc < 128) ? dstu : dst; ob[(cc < 128) ? offu : i * 512] = f2bf(acc[r]); }
;             }
;         }
	v_fma_f32 v68, v68, v38, -v2
	s_waitcnt lgkmcnt(14)
	v_fma_f32 v69, v69, v39, -v3
	s_waitcnt lgkmcnt(13)
	v_fma_f32 v70, v70, v40, -v4
	s_waitcnt lgkmcnt(12)
	v_fma_f32 v71, v71, v41, -v5
	s_waitcnt lgkmcnt(11)
	v_fma_f32 v72, v72, v42, -v6
	s_waitcnt lgkmcnt(10)
	v_fma_f32 v73, v73, v43, -v7
	s_waitcnt lgkmcnt(9)
	v_fma_f32 v74, v74, v44, -v8
	s_waitcnt lgkmcnt(8)
	v_fma_f32 v75, v75, v45, -v9
	s_waitcnt lgkmcnt(7)
	v_fma_f32 v76, v76, v46, -v10
	s_waitcnt lgkmcnt(6)
	v_fma_f32 v77, v77, v47, -v11
	s_waitcnt lgkmcnt(5)
	v_fma_f32 v78, v78, v48, -v12
	s_waitcnt lgkmcnt(4)
	v_fma_f32 v79, v79, v49, -v13
	s_waitcnt lgkmcnt(3)
	v_fma_f32 v80, v80, v50, -v14
	s_waitcnt lgkmcnt(2)
	v_fma_f32 v81, v81, v51, -v15
	s_waitcnt lgkmcnt(1)
	v_fma_f32 v82, v82, v52, -v16
	s_waitcnt lgkmcnt(0)
	v_fma_f32 v83, v83, v53, -v17
	ds_read_b128 v[38:41], v62 offset:13520
	ds_read_b128 v[20:23], v62 offset:13792
	s_waitcnt lgkmcnt(1)
	v_fma_f32 v69, -v38, v68, v69
	ds_read_b128 v[38:41], v62 offset:14064
	s_waitcnt lgkmcnt(1)
	v_fma_f32 v70, -v20, v68, v70
	v_fma_f32 v70, -v21, v69, v70
	ds_read_b128 v[20:23], v62 offset:14336
	s_waitcnt lgkmcnt(1)
	v_fma_f32 v71, -v38, v68, v71
	v_fma_f32 v71, -v39, v69, v71
	v_fma_f32 v71, -v40, v70, v71
	ds_read_b128 v[38:41], v62 offset:14608
	ds_read_b128 v[42:45], v62 offset:14624
	s_waitcnt lgkmcnt(2)
	v_fma_f32 v72, -v20, v68, v72
	v_fma_f32 v72, -v21, v69, v72
	v_fma_f32 v72, -v22, v70, v72
	v_fma_f32 v72, -v23, v71, v72
	ds_read_b128 v[20:23], v62 offset:14880
	ds_read_b128 v[24:27], v62 offset:14896
	s_waitcnt lgkmcnt(3)
	v_fma_f32 v73, -v38, v68, v73
	v_fma_f32 v73, -v39, v69, v73
	v_fma_f32 v73, -v40, v70, v73
	v_fma_f32 v73, -v41, v71, v73
	s_waitcnt lgkmcnt(2)
	v_fma_f32 v73, -v42, v72, v73
	ds_read_b128 v[38:41], v62 offset:15152
	ds_read_b128 v[42:45], v62 offset:15168
	s_waitcnt lgkmcnt(3)
	v_fma_f32 v74, -v20, v68, v74
	v_fma_f32 v74, -v21, v69, v74
	v_fma_f32 v74, -v22, v70, v74
	v_fma_f32 v74, -v23, v71, v74
	s_waitcnt lgkmcnt(2)
	v_fma_f32 v74, -v24, v72, v74
	v_fma_f32 v74, -v25, v73, v74
	ds_read_b128 v[20:23], v62 offset:15424
	ds_read_b128 v[24:27], v62 offset:15440
	s_waitcnt lgkmcnt(3)
	v_fma_f32 v75, -v38, v68, v75
	v_fma_f32 v75, -v39, v69, v75
	v_fma_f32 v75, -v40, v70, v75
	v_fma_f32 v75, -v41, v71, v75
	s_waitcnt lgkmcnt(2)
	v_fma_f32 v75, -v42, v72, v75
	v_fma_f32 v75, -v43, v73, v75
	v_fma_f32 v75, -v44, v74, v75
	ds_read_b128 v[38:41], v62 offset:15696
	ds_read_b128 v[42:45], v62 offset:15712
	ds_read_b128 v[46:49], v62 offset:15728
	s_waitcnt lgkmcnt(4)
	v_fma_f32 v76, -v20, v68, v76
	v_fma_f32 v76, -v21, v69, v76
	v_fma_f32 v76, -v22, v70, v76
	v_fma_f32 v76, -v23, v71, v76
	s_waitcnt lgkmcnt(3)
	v_fma_f32 v76, -v24, v72, v76
	v_fma_f32 v76, -v25, v73, v76
	v_fma_f32 v76, -v26, v74, v76
	v_fma_f32 v76, -v27, v75, v76
	ds_read_b128 v[20:23], v62 offset:15968
	ds_read_b128 v[24:27], v62 offset:15984
	ds_read_b128 v[28:31], v62 offset:16000
	s_waitcnt lgkmcnt(5)
	v_fma_f32 v77, -v38, v68, v77
	v_fma_f32 v77, -v39, v69, v77
	v_fma_f32 v77, -v40, v70, v77
	v_fma_f32 v77, -v41, v71, v77
	s_waitcnt lgkmcnt(4)
	v_fma_f32 v77, -v42, v72, v77
	v_fma_f32 v77, -v43, v73, v77
	v_fma_f32 v77, -v44, v74, v77
	v_fma_f32 v77, -v45, v75, v77
	s_waitcnt lgkmcnt(3)
	v_fma_f32 v77, -v46, v76, v77
	ds_read_b128 v[38:41], v62 offset:16240
	ds_read_b128 v[42:45], v62 offset:16256
	ds_read_b128 v[46:49], v62 offset:16272
	s_waitcnt lgkmcnt(5)
	v_fma_f32 v78, -v20, v68, v78
	v_fma_f32 v78, -v21, v69, v78
	v_fma_f32 v78, -v22, v70, v78
	v_fma_f32 v78, -v23, v71, v78
	s_waitcnt lgkmcnt(4)
; #define LAS __attribute__((address_space(3)))
; __device__ __forceinline__ float bf2f(bf16_t h) { return __uint_as_float(((unsigned)h) << 16); }
; __device__ __forceinline__ bf16_t f2bf(float f) { return (bf16_t)(cvt_pk(f, 0.f) & 0xffffu); }
; __device__ __forceinline__ void gdn_intra_item(const Ctx& a, int l, int h, int c, LAS unsigned char* lds) {
;     ...
;     if (tid < 256) {
;         const int cc = tid, d = cc & 127;
;         LAS float* xc = vf + cc;
;         bf16_t* dst = (bf16_t*)(a.ws + B_GW) + (size_t)t0 * 512 + h * 128 + d;
;         bf16_t* dstu = (bf16_t*)(a.ws + B_GU) + ((size_t)((h * 128 + c) * 4 + (d >> 5)) * 2) * 1024 + (d & 31) * 16;
; #pragma unroll 1
;         for (int bs = 0; bs < 64; bs += 16) {
;             float acc[16];
;             if (cc < 128) {
; #pragma unroll
;                 for (int r = 0; r < 16; ++r) { const int i = bs + r; acc[r] = xc[i * 256] * be[i]; }
;             } else {
; #pragma unroll
;                 for (int r = 0; r < 16; ++r) { const int i = bs + r; acc[r] = bf2f(kb[i * 136 + d]) * rkv[i] * be[i] * eg[i]; }
;             }
; #pragma unroll 1
;             for (int j = 0; j < bs; j += 4) {
;                 const float x0 = xc[(j + 0) * 256], x1 = xc[(j + 1) * 256], x2 = xc[(j + 2) * 256], x3 = xc[(j + 3) * 256];
; #pragma unroll
;                 for (int r = 0; r < 16; ++r) {
;                     f32x4 av = *(const LAS f32x4*)(Am + (bs + r) * 68 + j);
;                     acc[r] -= av[0] * x0 + av[1] * x1 + av[2] * x2 + av[3] * x3;
;                 }
;             }
; #pragma unroll
;             for (int r = 0; r < 16; ++r) {
; #pragma unroll
;                 for (int c4 = 0; c4 < (r + 3) / 4; ++c4) {
;                     f32x4 av = *(const LAS f32x4*)(Am + (bs + r) * 68 + bs + c4 * 4);
; #pragma unroll
;                     for (int e = 0; e < 4; ++e) if (c4 * 4 + e < r) acc[r] -= av[e] * acc[c4 * 4 + e];
;                 }
;                 const int i = bs + r;
;                 xc[i * 256] = acc[r];
;                 { const int i32 = i & 31; const int offu = (i >> 5) * 1024 + ((i32 >> 2) & 1) * 512 + (i32 >> 3) * 4 + (i & 3);
;                   bf16_t* ob = (cc < 128) ? dstu : dst; ob[(cc < 128) ? offu : i * 512] = f2bf(acc[r]); }
;             }
;         }
	v_fma_f32 v78, -v24, v72, v78
	v_fma_f32 v78, -v25, v73, v78
	v_fma_f32 v78, -v26, v74, v78
	v_fma_f32 v78, -v27, v75, v78
	s_waitcnt lgkmcnt(3)
	v_fma_f32 v78, -v28, v76, v78
	v_fma_f32 v78, -v29, v77, v78
	ds_read_b128 v[20:23], v62 offset:16512
	ds_read_b128 v[24:27], v62 offset:16528
	ds_read_b128 v[28:31], v62 offset:16544
	s_waitcnt lgkmcnt(5)
	v_fma_f32 v79, -v38, v68, v79
	v_fma_f32 v79, -v39, v69, v79
	v_fma_f32 v79, -v40, v70, v79
	v_fma_f32 v79, -v41, v71, v79
	s_waitcnt lgkmcnt(4)
	v_fma_f32 v79, -v42, v72, v79
	v_fma_f32 v79, -v43, v73, v79
	v_fma_f32 v79, -v44, v74, v79
	v_fma_f32 v79, -v45, v75, v79
	s_waitcnt lgkmcnt(3)
	v_fma_f32 v79, -v46, v76, v79
	v_fma_f32 v79, -v47, v77, v79
	v_fma_f32 v79, -v48, v78, v79
	ds_read_b128 v[38:41], v62 offset:16784
	ds_read_b128 v[42:45], v62 offset:16800
	ds_read_b128 v[46:49], v62 offset:16816
	ds_read_b128 v[50:53], v62 offset:16832
	s_waitcnt lgkmcnt(6)
	v_fma_f32 v80, -v20, v68, v80
	v_fma_f32 v80, -v21, v69, v80
	v_fma_f32 v80, -v22, v70, v80
	v_fma_f32 v80, -v23, v71, v80
	s_waitcnt lgkmcnt(5)
	v_fma_f32 v80, -v24, v72, v80
	v_fma_f32 v80, -v25, v73, v80
	v_fma_f32 v80, -v26, v74, v80
	v_fma_f32 v80, -v27, v75, v80
	s_waitcnt lgkmcnt(4)
	v_fma_f32 v80, -v28, v76, v80
	v_fma_f32 v80, -v29, v77, v80
	v_fma_f32 v80, -v30, v78, v80
	v_fma_f32 v80, -v31, v79, v80
	ds_read_b128 v[20:23], v62 offset:17056
	ds_read_b128 v[24:27], v62 offset:17072
	ds_read_b128 v[28:31], v62 offset:17088
	ds_read_b128 v[32:35], v62 offset:17104
	s_waitcnt lgkmcnt(7)
	v_fma_f32 v81, -v38, v68, v81
	v_fma_f32 v81, -v39, v69, v81
	v_fma_f32 v81, -v40, v70, v81
	v_fma_f32 v81, -v41, v71, v81
	s_waitcnt lgkmcnt(6)
	v_fma_f32 v81, -v42, v72, v81
	v_fma_f32 v81, -v43, v73, v81
	v_fma_f32 v81, -v44, v74, v81
	v_fma_f32 v81, -v45, v75, v81
	s_waitcnt lgkmcnt(5)
	v_fma_f32 v81, -v46, v76, v81
	v_fma_f32 v81, -v47, v77, v81
	v_fma_f32 v81, -v48, v78, v81
	v_fma_f32 v81, -v49, v79, v81
	s_waitcnt lgkmcnt(4)
	v_fma_f32 v81, -v50, v80, v81
	ds_read_b128 v[38:41], v62 offset:17328
	ds_read_b128 v[42:45], v62 offset:17344
	ds_read_b128 v[46:49], v62 offset:17360
	ds_read_b128 v[50:53], v62 offset:17376
	s_waitcnt lgkmcnt(7)
	v_fma_f32 v82, -v20, v68, v82
	v_fma_f32 v82, -v21, v69, v82
	v_fma_f32 v82, -v22, v70, v82
	v_fma_f32 v82, -v23, v71, v82
	s_waitcnt lgkmcnt(6)
	v_fma_f32 v82, -v24, v72, v82
	v_fma_f32 v82, -v25, v73, v82
	v_fma_f32 v82, -v26, v74, v82
	v_fma_f32 v82, -v27, v75, v82
	s_waitcnt lgkmcnt(5)
	v_fma_f32 v82, -v28, v76, v82
	v_fma_f32 v82, -v29, v77, v82
	v_fma_f32 v82, -v30, v78, v82
	v_fma_f32 v82, -v31, v79, v82
	s_waitcnt lgkmcnt(4)
	v_fma_f32 v82, -v32, v80, v82
	v_fma_f32 v82, -v33, v81, v82
	s_waitcnt lgkmcnt(3)
	v_fma_f32 v83, -v38, v68, v83
	v_fma_f32 v83, -v39, v69, v83
	v_fma_f32 v83, -v40, v70, v83
	v_fma_f32 v83, -v41, v71, v83
	s_waitcnt lgkmcnt(2)
	v_fma_f32 v83, -v42, v72, v83
	v_fma_f32 v83, -v43, v73, v83
	v_fma_f32 v83, -v44, v74, v83
	v_fma_f32 v83, -v45, v75, v83
	s_waitcnt lgkmcnt(1)
	v_fma_f32 v83, -v46, v76, v83
	v_fma_f32 v83, -v47, v77, v83
	v_fma_f32 v83, -v48, v78, v83
	v_fma_f32 v83, -v49, v79, v83
	s_waitcnt lgkmcnt(0)
	v_fma_f32 v83, -v50, v80, v83
	v_fma_f32 v83, -v51, v81, v83
	v_fma_f32 v83, -v52, v82, v83
	v_cvt_pk_bf16_f32 v2, v68, v69
	v_cvt_pk_bf16_f32 v3, v70, v71
	v_cvt_pk_bf16_f32 v4, v76, v77
	v_cvt_pk_bf16_f32 v5, v78, v79
	global_store_dwordx4 v60, v[2:5], s[36:37] offset:2064
	v_cvt_pk_bf16_f32 v6, v72, v73
	v_cvt_pk_bf16_f32 v7, v74, v75
	v_cvt_pk_bf16_f32 v8, v80, v81
	v_cvt_pk_bf16_f32 v9, v82, v83
	global_store_dwordx4 v60, v[6:9], s[36:37] offset:3088
	s_waitcnt lgkmcnt(0)
	s_branch .LBB0_339

; #define LAS __attribute__((address_space(3)))
; __device__ __forceinline__ float bf2f(bf16_t h) { return __uint_as_float(((unsigned)h) << 16); }
; __device__ __forceinline__ bf16_t f2bf(float f) { return (bf16_t)(cvt_pk(f, 0.f) & 0xffffu); }
; __device__ __forceinline__ void gdn_intra_item(const Ctx& a, int l, int h, int c, LAS unsigned char* lds) {
;     ...
;     if (tid < 256) {
;         const int cc = tid, d = cc & 127;
;         LAS float* xc = vf + cc;
;         bf16_t* dst = (bf16_t*)(a.ws + B_GW) + (size_t)t0 * 512 + h * 128 + d;
;         bf16_t* dstu = (bf16_t*)(a.ws + B_GU) + ((size_t)((h * 128 + c) * 4 + (d >> 5)) * 2) * 1024 + (d & 31) * 16;
; #pragma unroll 1
;         for (int bs = 0; bs < 64; bs += 16) {
;             float acc[16];
;             if (cc < 128) {
; #pragma unroll
;                 for (int r = 0; r < 16; ++r) { const int i = bs + r; acc[r] = xc[i * 256] * be[i]; }
;             } else {
; #pragma unroll
;                 for (int r = 0; r < 16; ++r) { const int i = bs + r; acc[r] = bf2f(kb[i * 136 + d]) * rkv[i] * be[i] * eg[i]; }
;             }
; #pragma unroll 1
;             for (int j = 0; j < bs; j += 4) {
;                 const float x0 = xc[(j + 0) * 256], x1 = xc[(j + 1) * 256], x2 = xc[(j + 2) * 256], x3 = xc[(j + 3) * 256];
; #pragma unroll
;                 for (int r = 0; r < 16; ++r) {
;                     f32x4 av = *(const LAS f32x4*)(Am + (bs + r) * 68 + j);
;                     acc[r] -= av[0] * x0 + av[1] * x1 + av[2] * x2 + av[3] * x3;
;                 }
;             }
; #pragma unroll
;             for (int r = 0; r < 16; ++r) {
; #pragma unroll
;                 for (int c4 = 0; c4 < (r + 3) / 4; ++c4) {
;                     f32x4 av = *(const LAS f32x4*)(Am + (bs + r) * 68 + bs + c4 * 4);
; #pragma unroll
;                     for (int e = 0; e < 4; ++e) if (c4 * 4 + e < r) acc[r] -= av[e] * acc[c4 * 4 + e];
;                 }
;                 const int i = bs + r;
;                 xc[i * 256] = acc[r];
;                 { const int i32 = i & 31; const int offu = (i >> 5) * 1024 + ((i32 >> 2) & 1) * 512 + (i32 >> 3) * 4 + (i & 3);
;                   bf16_t* ob = (cc < 128) ? dstu : dst; ob[(cc < 128) ? offu : i * 512] = f2bf(acc[r]); }
;             }
;         }
.Lgi_W:
	s_lshl_b32 s6, s1, 16
	s_lshl_b32 s8, s0, 8
	s_add_u32 s6, s6, s8
	s_add_u32 s36, s16, 0xf0f4200
	s_addc_u32 s37, s17, 0
	s_add_u32 s36, s36, s6
	s_addc_u32 s37, s37, 0
	s_nop 4
	v_subrev_u32 v64, 0x80, v63
	v_lshlrev_b32 v61, 1, v64
	v_add_u32 v59, 17408, v61
	ds_read_b128 v[38:41], v62 offset:17664
	ds_read_b128 v[42:45], v62 offset:17680
	ds_read_b128 v[46:49], v62 offset:17696
	ds_read_b128 v[50:53], v62 offset:17712
	ds_read_u16 v68, v59 offset:0
	ds_read_u16 v69, v59 offset:272
	ds_read_u16 v70, v59 offset:544
	ds_read_u16 v71, v59 offset:816
	ds_read_u16 v72, v59 offset:1088
	ds_read_u16 v73, v59 offset:1360
	ds_read_u16 v74, v59 offset:1632
	ds_read_u16 v75, v59 offset:1904
	ds_read_u16 v76, v59 offset:2176
	ds_read_u16 v77, v59 offset:2448
	ds_read_u16 v78, v59 offset:2720
	ds_read_u16 v79, v59 offset:2992
	ds_read_u16 v80, v59 offset:3264
	ds_read_u16 v81, v59 offset:3536
	ds_read_u16 v82, v59 offset:3808
	ds_read_u16 v83, v59 offset:4080
	ds_read_b128 v[20:23], v62 offset:19200
	ds_read_b128 v[24:27], v62 offset:19216
	ds_read_b128 v[28:31], v62 offset:19232
	ds_read_b128 v[32:35], v62 offset:19248
	s_waitcnt lgkmcnt(15)
	v_lshlrev_b32 v68, 16, v68
	s_waitcnt lgkmcnt(15)
	v_lshlrev_b32 v69, 16, v69
	s_waitcnt lgkmcnt(15)
	v_lshlrev_b32 v70, 16, v70
	s_waitcnt lgkmcnt(15)
	v_lshlrev_b32 v71, 16, v71
	s_waitcnt lgkmcnt(15)
	v_lshlrev_b32 v72, 16, v72
	s_waitcnt lgkmcnt(14)
	v_lshlrev_b32 v73, 16, v73
	s_waitcnt lgkmcnt(13)
	v_lshlrev_b32 v74, 16, v74
	s_waitcnt lgkmcnt(12)
	v_lshlrev_b32 v75, 16, v75
	s_waitcnt lgkmcnt(11)
	v_lshlrev_b32 v76, 16, v76
	s_waitcnt lgkmcnt(10)
	v_lshlrev_b32 v77, 16, v77
	s_waitcnt lgkmcnt(9)
	v_lshlrev_b32 v78, 16, v78
	s_waitcnt lgkmcnt(8)
	v_lshlrev_b32 v79, 16, v79
	s_waitcnt lgkmcnt(7)
	v_lshlrev_b32 v80, 16, v80
	s_waitcnt lgkmcnt(6)
	v_lshlrev_b32 v81, 16, v81
	s_waitcnt lgkmcnt(5)
	v_lshlrev_b32 v82, 16, v82
	s_waitcnt lgkmcnt(4)
	v_lshlrev_b32 v83, 16, v83
	s_waitcnt lgkmcnt(3)
	v_mul_f32 v68, v68, v20
	v_mul_f32 v69, v69, v21
	v_mul_f32 v70, v70, v22
	v_mul_f32 v71, v71, v23
	s_waitcnt lgkmcnt(2)
	v_mul_f32 v72, v72, v24
	v_mul_f32 v73, v73, v25
	v_mul_f32 v74, v74, v26
	v_mul_f32 v75, v75, v27
	s_waitcnt lgkmcnt(1)
	v_mul_f32 v76, v76, v28
	v_mul_f32 v77, v77, v29
	v_mul_f32 v78, v78, v30
	v_mul_f32 v79, v79, v31
	s_waitcnt lgkmcnt(0)
	v_mul_f32 v80, v80, v32
	v_mul_f32 v81, v81, v33
	v_mul_f32 v82, v82, v34
	v_mul_f32 v83, v83, v35
	ds_read_b128 v[20:23], v62 offset:19456
	ds_read_b128 v[24:27], v62 offset:19472
	ds_read_b128 v[28:31], v62 offset:19488
	ds_read_b128 v[32:35], v62 offset:19504
	v_mul_f32 v68, v68, v38
	v_mul_f32 v69, v69, v39
	v_mul_f32 v70, v70, v40
	v_mul_f32 v71, v71, v41
	v_mul_f32 v72, v72, v42
	v_mul_f32 v73, v73, v43
	v_mul_f32 v74, v74, v44
	v_mul_f32 v75, v75, v45
	v_mul_f32 v76, v76, v46
	v_mul_f32 v77, v77, v47
	v_mul_f32 v78, v78, v48
	v_mul_f32 v79, v79, v49
	v_mul_f32 v80, v80, v50
	v_mul_f32 v81, v81, v51
	v_mul_f32 v82, v82, v52
	v_mul_f32 v83, v83, v53
	s_waitcnt lgkmcnt(3)
	v_mul_f32 v68, v68, v20
	v_mul_f32 v69, v69, v21
	v_mul_f32 v70, v70, v22
	v_mul_f32 v71, v71, v23
	s_waitcnt lgkmcnt(2)
	v_mul_f32 v72, v72, v24
	v_mul_f32 v73, v73, v25
	v_mul_f32 v74, v74, v26
	v_mul_f32 v75, v75, v27
	s_waitcnt lgkmcnt(1)
	v_mul_f32 v76, v76, v28
	v_mul_f32 v77, v77, v29
	v_mul_f32 v78, v78, v30
	v_mul_f32 v79, v79, v31
	s_waitcnt lgkmcnt(0)
	v_mul_f32 v80, v80, v32
	v_mul_f32 v81, v81, v33
	v_mul_f32 v82, v82, v34
	v_mul_f32 v83, v83, v35
	ds_read_b128 v[38:41], v62 offset:272
	ds_read_b128 v[20:23], v62 offset:544
	s_waitcnt lgkmcnt(1)
	v_fma_f32 v69, -v38, v68, v69
	ds_read_b128 v[38:41], v62 offset:816
	s_waitcnt lgkmcnt(1)
	v_fma_f32 v70, -v20, v68, v70
	v_fma_f32 v70, -v21, v69, v70
	ds_read_b128 v[20:23], v62 offset:1088
	s_waitcnt lgkmcnt(1)
	v_fma_f32 v71, -v38, v68, v71
	v_fma_f32 v71, -v39, v69, v71
	v_fma_f32 v71, -v40, v70, v71
	ds_read_b128 v[38:41], v62 offset:1360
	ds_read_b128 v[42:45], v62 offset:1376
	s_waitcnt lgkmcnt(2)
	v_fma_f32 v72, -v20, v68, v72
	v_fma_f32 v72, -v21, v69, v72
	v_fma_f32 v72, -v22, v70, v72
	v_fma_f32 v72, -v23, v71, v72
	ds_read_b128 v[20:23], v62 offset:1632
	ds_read_b128 v[24:27], v62 offset:1648
	s_waitcnt lgkmcnt(3)
	v_fma_f32 v73, -v38, v68, v73
	v_fma_f32 v73, -v39, v69, v73
	v_fma_f32 v73, -v40, v70, v73
	v_fma_f32 v73, -v41, v71, v73
	s_waitcnt lgkmcnt(2)
	v_fma_f32 v73, -v42, v72, v73
	ds_read_b128 v[38:41], v62 offset:1904
	ds_read_b128 v[42:45], v62 offset:1920
	s_waitcnt lgkmcnt(3)
	v_fma_f32 v74, -v20, v68, v74
	v_fma_f32 v74, -v21, v69, v74
	v_fma_f32 v74, -v22, v70, v74
	v_fma_f32 v74, -v23, v71, v74
	s_waitcnt lgkmcnt(2)
	v_fma_f32 v74, -v24, v72, v74
	v_fma_f32 v74, -v25, v73, v74
	ds_read_b128 v[20:23], v62 offset:2176
	ds_read_b128 v[24:27], v62 offset:2192
	s_waitcnt lgkmcnt(3)
	v_fma_f32 v75, -v38, v68, v75
	v_fma_f32 v75, -v39, v69, v75
	v_fma_f32 v75, -v40, v70, v75
	v_fma_f32 v75, -v41, v71, v75
	s_waitcnt lgkmcnt(2)
	v_fma_f32 v75, -v42, v72, v75
	v_fma_f32 v75, -v43, v73, v75
	v_fma_f32 v75, -v44, v74, v75
	ds_read_b128 v[38:41], v62 offset:2448
	ds_read_b128 v[42:45], v62 offset:2464
	ds_read_b128 v[46:49], v62 offset:2480
	s_waitcnt lgkmcnt(4)
	v_fma_f32 v76, -v20, v68, v76
	v_fma_f32 v76, -v21, v69, v76
	v_fma_f32 v76, -v22, v70, v76
	v_fma_f32 v76, -v23, v71, v76
	s_waitcnt lgkmcnt(3)
	v_fma_f32 v76, -v24, v72, v76
	v_fma_f32 v76, -v25, v73, v76
	v_fma_f32 v76, -v26, v74, v76
	v_fma_f32 v76, -v27, v75, v76
	ds_read_b128 v[20:23], v62 offset:2720
	ds_read_b128 v[24:27], v62 offset:2736
	ds_read_b128 v[28:31], v62 offset:2752
	s_waitcnt lgkmcnt(5)
	v_fma_f32 v77, -v38, v68, v77
	v_fma_f32 v77, -v39, v69, v77
	v_fma_f32 v77, -v40, v70, v77
	v_fma_f32 v77, -v41, v71, v77
	s_waitcnt lgkmcnt(4)
	v_fma_f32 v77, -v42, v72, v77
	v_fma_f32 v77, -v43, v73, v77
	v_fma_f32 v77, -v44, v74, v77
	v_fma_f32 v77, -v45, v75, v77
	s_waitcnt lgkmcnt(3)
	v_fma_f32 v77, -v46, v76, v77
	ds_read_b128 v[38:41], v62 offset:2992
	ds_read_b128 v[42:45], v62 offset:3008
	ds_read_b128 v[46:49], v62 offset:3024
	s_waitcnt lgkmcnt(5)
	v_fma_f32 v78, -v20, v68, v78
	v_fma_f32 v78, -v21, v69, v78
	v_fma_f32 v78, -v22, v70, v78
	v_fma_f32 v78, -v23, v71, v78
	s_waitcnt lgkmcnt(4)
	v_fma_f32 v78, -v24, v72, v78
	v_fma_f32 v78, -v25, v73, v78
	v_fma_f32 v78, -v26, v74, v78
	v_fma_f32 v78, -v27, v75, v78
	s_waitcnt lgkmcnt(3)
	v_fma_f32 v78, -v28, v76, v78
	v_fma_f32 v78, -v29, v77, v78
	ds_read_b128 v[20:23], v62 offset:3264
	ds_read_b128 v[24:27], v62 offset:3280
	ds_read_b128 v[28:31], v62 offset:3296
	s_waitcnt lgkmcnt(5)
	v_fma_f32 v79, -v38, v68, v79
	v_fma_f32 v79, -v39, v69, v79
	v_fma_f32 v79, -v40, v70, v79
	v_fma_f32 v79, -v41, v71, v79
	s_waitcnt lgkmcnt(4)
	v_fma_f32 v79, -v42, v72, v79
	v_fma_f32 v79, -v43, v73, v79
	v_fma_f32 v79, -v44, v74, v79
	v_fma_f32 v79, -v45, v75, v79
	s_waitcnt lgkmcnt(3)
	v_fma_f32 v79, -v46, v76, v79
	v_fma_f32 v79, -v47, v77, v79
	v_fma_f32 v79, -v48, v78, v79
	ds_read_b128 v[38:41], v62 offset:3536
	ds_read_b128 v[42:45], v62 offset:3552
	ds_read_b128 v[46:49], v62 offset:3568
	ds_read_b128 v[50:53], v62 offset:3584
	s_waitcnt lgkmcnt(6)
	v_fma_f32 v80, -v20, v68, v80
	v_fma_f32 v80, -v21, v69, v80
	v_fma_f32 v80, -v22, v70, v80
	v_fma_f32 v80, -v23, v71, v80
	s_waitcnt lgkmcnt(5)
	v_fma_f32 v80, -v24, v72, v80
	v_fma_f32 v80, -v25, v73, v80
	v_fma_f32 v80, -v26, v74, v80
	v_fma_f32 v80, -v27, v75, v80
	s_waitcnt lgkmcnt(4)
	v_fma_f32 v80, -v28, v76, v80
	v_fma_f32 v80, -v29, v77, v80
	v_fma_f32 v80, -v30, v78, v80
	v_fma_f32 v80, -v31, v79, v80
	ds_read_b128 v[20:23], v62 offset:3808
	ds_read_b128 v[24:27], v62 offset:3824
	ds_read_b128 v[28:31], v62 offset:3840
	ds_read_b128 v[32:35], v62 offset:3856
	s_waitcnt lgkmcnt(7)
	v_fma_f32 v81, -v38, v68, v81
	v_fma_f32 v81, -v39, v69, v81
	v_fma_f32 v81, -v40, v70, v81
	v_fma_f32 v81, -v41, v71, v81
	s_waitcnt lgkmcnt(6)
	v_fma_f32 v81, -v42, v72, v81
	v_fma_f32 v81, -v43, v73, v81
	v_fma_f32 v81, -v44, v74, v81
	v_fma_f32 v81, -v45, v75, v81
	s_waitcnt lgkmcnt(5)
	v_fma_f32 v81, -v46, v76, v81
	v_fma_f32 v81, -v47, v77, v81
	v_fma_f32 v81, -v48, v78, v81
	v_fma_f32 v81, -v49, v79, v81
	s_waitcnt lgkmcnt(4)
	v_fma_f32 v81, -v50, v80, v81
	ds_read_b128 v[38:41], v62 offset:4080
	ds_read_b128 v[42:45], v62 offset:4096
	ds_read_b128 v[46:49], v62 offset:4112
	ds_read_b128 v[50:53], v62 offset:4128
	s_waitcnt lgkmcnt(7)
	v_fma_f32 v82, -v20, v68, v82
	v_fma_f32 v82, -v21, v69, v82
	v_fma_f32 v82, -v22, v70, v82
	v_fma_f32 v82, -v23, v71, v82
	s_waitcnt lgkmcnt(6)
	v_fma_f32 v82, -v24, v72, v82
	v_fma_f32 v82, -v25, v73, v82
	v_fma_f32 v82, -v26, v74, v82
	v_fma_f32 v82, -v27, v75, v82
	s_waitcnt lgkmcnt(5)
	v_fma_f32 v82, -v28, v76, v82
	v_fma_f32 v82, -v29, v77, v82
	v_fma_f32 v82, -v30, v78, v82
	v_fma_f32 v82, -v31, v79, v82
	s_waitcnt lgkmcnt(4)
	v_fma_f32 v82, -v32, v80, v82
	v_fma_f32 v82, -v33, v81, v82
	s_waitcnt lgkmcnt(3)
	v_fma_f32 v83, -v38, v68, v83
	v_fma_f32 v83, -v39, v69, v83
	v_fma_f32 v83, -v40, v70, v83
	v_fma_f32 v83, -v41, v71, v83
	s_waitcnt lgkmcnt(2)
	v_fma_f32 v83, -v42, v72, v83
	v_fma_f32 v83, -v43, v73, v83
	v_fma_f32 v83, -v44, v74, v83
	v_fma_f32 v83, -v45, v75, v83
	s_waitcnt lgkmcnt(1)
	v_fma_f32 v83, -v46, v76, v83
	v_fma_f32 v83, -v47, v77, v83
	v_fma_f32 v83, -v48, v78, v83
	v_fma_f32 v83, -v49, v79, v83
	s_waitcnt lgkmcnt(0)
	v_fma_f32 v83, -v50, v80, v83
	v_fma_f32 v83, -v51, v81, v83
	v_fma_f32 v83, -v52, v82, v83
	ds_write_b32 v58, v68 offset:0
	ds_write_b32 v58, v69 offset:1024
	ds_write_b32 v58, v70 offset:2048
	ds_write_b32 v58, v71 offset:3072
	ds_write_b32 v58, v72 offset:4096
	ds_write_b32 v58, v73 offset:5120
	ds_write_b32 v58, v74 offset:6144
	ds_write_b32 v58, v75 offset:7168
	ds_write_b32 v58, v76 offset:8192
	ds_write_b32 v58, v77 offset:9216
	ds_write_b32 v58, v78 offset:10240
	ds_write_b32 v58, v79 offset:11264
	ds_write_b32 v58, v80 offset:12288
	ds_write_b32 v58, v81 offset:13312
	ds_write_b32 v58, v82 offset:14336
	ds_write_b32 v58, v83 offset:15360
	v_add_u32 v64, 0x0, v61
	v_cvt_pk_bf16_f32 v2, v68, v68
	global_store_short v64, v2, s[36:37] offset:0
	v_cvt_pk_bf16_f32 v3, v69, v69
	global_store_short v64, v3, s[36:37] offset:1024
	v_cvt_pk_bf16_f32 v4, v70, v70
	global_store_short v64, v4, s[36:37] offset:2048
	v_cvt_pk_bf16_f32 v5, v71, v71
	global_store_short v64, v5, s[36:37] offset:3072
	v_add_u32 v64, 0x1000, v61
	v_cvt_pk_bf16_f32 v6, v72, v72
	global_store_short v64, v6, s[36:37] offset:0
	v_cvt_pk_bf16_f32 v7, v73, v73
	global_store_short v64, v7, s[36:37] offset:1024
	v_cvt_pk_bf16_f32 v8, v74, v74
	global_store_short v64, v8, s[36:37] offset:2048
	v_cvt_pk_bf16_f32 v9, v75, v75
	global_store_short v64, v9, s[36:37] offset:3072
	v_add_u32 v64, 0x2000, v61
	v_cvt_pk_bf16_f32 v2, v76, v76
	global_store_short v64, v2, s[36:37] offset:0
	v_cvt_pk_bf16_f32 v3, v77, v77
	global_store_short v64, v3, s[36:37] offset:1024
	v_cvt_pk_bf16_f32 v4, v78, v78
	global_store_short v64, v4, s[36:37] offset:2048
	v_cvt_pk_bf16_f32 v5, v79, v79
	global_store_short v64, v5, s[36:37] offset:3072
	v_add_u32 v64, 0x3000, v61
	v_cvt_pk_bf16_f32 v6, v80, v80
	global_store_short v64, v6, s[36:37] offset:0
	v_cvt_pk_bf16_f32 v7, v81, v81
	global_store_short v64, v7, s[36:37] offset:1024
	v_cvt_pk_bf16_f32 v8, v82, v82
	global_store_short v64, v8, s[36:37] offset:2048
	v_cvt_pk_bf16_f32 v9, v83, v83
	global_store_short v64, v9, s[36:37] offset:3072
	ds_read_b32 v36, v54 offset:4352
	ds_read_b32 v38, v55 offset:0
	ds_read_b32 v39, v55 offset:64
	ds_read_b32 v40, v55 offset:128
	ds_read_b32 v41, v55 offset:192
	ds_read_b32 v19, v54 offset:4368
	ds_read_b32 v42, v55 offset:4096
	ds_read_b32 v43, v55 offset:4160
	ds_read_b32 v44, v55 offset:4224
	ds_read_b32 v45, v55 offset:4288
	s_waitcnt lgkmcnt(8)
	v_mfma_f32_16x16x4_f32 v[20:23], v36, v38, 0
	s_waitcnt lgkmcnt(7)
	v_mfma_f32_16x16x4_f32 v[24:27], v36, v39, 0
	s_waitcnt lgkmcnt(6)
	v_mfma_f32_16x16x4_f32 v[28:31], v36, v40, 0
	s_waitcnt lgkmcnt(5)
	v_mfma_f32_16x16x4_f32 v[32:35], v36, v41, 0
	ds_read_b32 v36, v54 offset:4384
	ds_read_b32 v38, v55 offset:8192
	ds_read_b32 v39, v55 offset:8256
	ds_read_b32 v40, v55 offset:8320
	ds_read_b32 v41, v55 offset:8384
	s_waitcnt lgkmcnt(8)
	v_mfma_f32_16x16x4_f32 v[20:23], v19, v42, v[20:23]
	s_waitcnt lgkmcnt(7)
	v_mfma_f32_16x16x4_f32 v[24:27], v19, v43, v[24:27]
	s_waitcnt lgkmcnt(6)
	v_mfma_f32_16x16x4_f32 v[28:31], v19, v44, v[28:31]
	s_waitcnt lgkmcnt(5)
	v_mfma_f32_16x16x4_f32 v[32:35], v19, v45, v[32:35]
	ds_read_b32 v19, v54 offset:4400
	ds_read_b32 v42, v55 offset:12288
	ds_read_b32 v43, v55 offset:12352
	ds_read_b32 v44, v55 offset:12416
	ds_read_b32 v45, v55 offset:12480
	s_waitcnt lgkmcnt(8)
	v_mfma_f32_16x16x4_f32 v[20:23], v36, v38, v[20:23]
	s_waitcnt lgkmcnt(7)
	v_mfma_f32_16x16x4_f32 v[24:27], v36, v39, v[24:27]
	s_waitcnt lgkmcnt(6)
	v_mfma_f32_16x16x4_f32 v[28:31], v36, v40, v[28:31]
	s_waitcnt lgkmcnt(5)
	v_mfma_f32_16x16x4_f32 v[32:35], v36, v41, v[32:35]
	s_waitcnt lgkmcnt(3)
	v_mfma_f32_16x16x4_f32 v[20:23], v19, v42, v[20:23]
	s_waitcnt lgkmcnt(2)
	v_mfma_f32_16x16x4_f32 v[24:27], v19, v43, v[24:27]
	s_waitcnt lgkmcnt(1)
	v_mfma_f32_16x16x4_f32 v[28:31], v19, v44, v[28:31]
	s_waitcnt lgkmcnt(0)
	v_mfma_f32_16x16x4_f32 v[32:35], v19, v45, v[32:35]
	s_nop 5
	ds_write_b128 v56, v[20:23] offset:0
	s_nop 0
	ds_write_b128 v56, v[24:27] offset:1280
	s_nop 0
	ds_write_b128 v56, v[28:31] offset:2560
	s_nop 0
	ds_write_b128 v56, v[32:35] offset:3840
	ds_read_b128 v[2:5], v57 offset:0
	ds_read_b128 v[6:9], v57 offset:16
	ds_read_b128 v[10:13], v57 offset:32
	ds_read_b128 v[14:17], v57 offset:48
	ds_read_b128 v[38:41], v62 offset:17728
	ds_read_b128 v[42:45], v62 offset:17744
	ds_read_b128 v[46:49], v62 offset:17760
	ds_read_b128 v[50:53], v62 offset:17776
	ds_read_u16 v68, v59 offset:4352
	ds_read_u16 v69, v59 offset:4624
	ds_read_u16 v70, v59 offset:4896
	ds_read_u16 v71, v59 offset:5168
	ds_read_u16 v72, v59 offset:5440
	ds_read_u16 v73, v59 offset:5712
	ds_read_u16 v74, v59 offset:5984
	ds_read_u16 v75, v59 offset:6256
	ds_read_u16 v76, v59 offset:6528
	ds_read_u16 v77, v59 offset:6800
	ds_read_u16 v78, v59 offset:7072
	ds_read_u16 v79, v59 offset:7344
	ds_read_u16 v80, v59 offset:7616
	ds_read_u16 v81, v59 offset:7888
	ds_read_u16 v82, v59 offset:8160
	ds_read_u16 v83, v59 offset:8432
	ds_read_b128 v[20:23], v62 offset:19264
	ds_read_b128 v[24:27], v62 offset:19280
	ds_read_b128 v[28:31], v62 offset:19296
	ds_read_b128 v[32:35], v62 offset:19312
	s_waitcnt lgkmcnt(15)
	v_lshlrev_b32 v68, 16, v68
	s_waitcnt lgkmcnt(15)
	v_lshlrev_b32 v69, 16, v69
	s_waitcnt lgkmcnt(15)
	v_lshlrev_b32 v70, 16, v70
	s_waitcnt lgkmcnt(15)
	v_lshlrev_b32 v71, 16, v71
	s_waitcnt lgkmcnt(15)
	v_lshlrev_b32 v72, 16, v72
	s_waitcnt lgkmcnt(14)
	v_lshlrev_b32 v73, 16, v73
	s_waitcnt lgkmcnt(13)
	v_lshlrev_b32 v74, 16, v74
	s_waitcnt lgkmcnt(12)
	v_lshlrev_b32 v75, 16, v75
	s_waitcnt lgkmcnt(11)
	v_lshlrev_b32 v76, 16, v76
	s_waitcnt lgkmcnt(10)
	v_lshlrev_b32 v77, 16, v77
	s_waitcnt lgkmcnt(9)
	v_lshlrev_b32 v78, 16, v78
	s_waitcnt lgkmcnt(8)
	v_lshlrev_b32 v79, 16, v79
	s_waitcnt lgkmcnt(7)
	v_lshlrev_b32 v80, 16, v80
	s_waitcnt lgkmcnt(6)
	v_lshlrev_b32 v81, 16, v81
	s_waitcnt lgkmcnt(5)
	v_lshlrev_b32 v82, 16, v82
	s_waitcnt lgkmcnt(4)
	v_lshlrev_b32 v83, 16, v83
	s_waitcnt lgkmcnt(3)
	v_mul_f32 v68, v68, v20
	v_mul_f32 v69, v69, v21
	v_mul_f32 v70, v70, v22
	v_mul_f32 v71, v71, v23
	s_waitcnt lgkmcnt(2)
	v_mul_f32 v72, v72, v24
	v_mul_f32 v73, v73, v25
	v_mul_f32 v74, v74, v26
	v_mul_f32 v75, v75, v27
	s_waitcnt lgkmcnt(1)
	v_mul_f32 v76, v76, v28
	v_mul_f32 v77, v77, v29
	v_mul_f32 v78, v78, v30
	v_mul_f32 v79, v79, v31
	s_waitcnt lgkmcnt(0)
	v_mul_f32 v80, v80, v32
	v_mul_f32 v81, v81, v33
	v_mul_f32 v82, v82, v34
	v_mul_f32 v83, v83, v35
	ds_read_b128 v[20:23], v62 offset:19520
	ds_read_b128 v[24:27], v62 offset:19536
	ds_read_b128 v[28:31], v62 offset:19552
	ds_read_b128 v[32:35], v62 offset:19568
	v_mul_f32 v68, v68, v38
	v_mul_f32 v69, v69, v39
	v_mul_f32 v70, v70, v40
	v_mul_f32 v71, v71, v41
	v_mul_f32 v72, v72, v42
	v_mul_f32 v73, v73, v43
	v_mul_f32 v74, v74, v44
	v_mul_f32 v75, v75, v45
	v_mul_f32 v76, v76, v46
	v_mul_f32 v77, v77, v47
	v_mul_f32 v78, v78, v48
	v_mul_f32 v79, v79, v49
	v_mul_f32 v80, v80, v50
	v_mul_f32 v81, v81, v51
	v_mul_f32 v82, v82, v52
	v_mul_f32 v83, v83, v53
	s_waitcnt lgkmcnt(3)
	v_fma_f32 v68, v68, v20, -v2
	v_fma_f32 v69, v69, v21, -v3
	v_fma_f32 v70, v70, v22, -v4
	v_fma_f32 v71, v71, v23, -v5
	s_waitcnt lgkmcnt(2)
	v_fma_f32 v72, v72, v24, -v6
	v_fma_f32 v73, v73, v25, -v7
	v_fma_f32 v74, v74, v26, -v8
	v_fma_f32 v75, v75, v27, -v9
	s_waitcnt lgkmcnt(1)
	v_fma_f32 v76, v76, v28, -v10
	v_fma_f32 v77, v77, v29, -v11
	v_fma_f32 v78, v78, v30, -v12
	v_fma_f32 v79, v79, v31, -v13
	s_waitcnt lgkmcnt(0)
	v_fma_f32 v80, v80, v32, -v14
	v_fma_f32 v81, v81, v33, -v15
	v_fma_f32 v82, v82, v34, -v16
	v_fma_f32 v83, v83, v35, -v17
	ds_read_b128 v[38:41], v62 offset:4688
	ds_read_b128 v[20:23], v62 offset:4960
	s_waitcnt lgkmcnt(1)
	v_fma_f32 v69, -v38, v68, v69
	ds_read_b128 v[38:41], v62 offset:5232
	s_waitcnt lgkmcnt(1)
	v_fma_f32 v70, -v20, v68, v70
	v_fma_f32 v70, -v21, v69, v70
	ds_read_b128 v[20:23], v62 offset:5504
	s_waitcnt lgkmcnt(1)
	v_fma_f32 v71, -v38, v68, v71
	v_fma_f32 v71, -v39, v69, v71
	v_fma_f32 v71, -v40, v70, v71
	ds_read_b128 v[38:41], v62 offset:5776
	ds_read_b128 v[42:45], v62 offset:5792
	s_waitcnt lgkmcnt(2)
	v_fma_f32 v72, -v20, v68, v72
	v_fma_f32 v72, -v21, v69, v72
	v_fma_f32 v72, -v22, v70, v72
	v_fma_f32 v72, -v23, v71, v72
	ds_read_b128 v[20:23], v62 offset:6048
	ds_read_b128 v[24:27], v62 offset:6064
	s_waitcnt lgkmcnt(3)
	v_fma_f32 v73, -v38, v68, v73
	v_fma_f32 v73, -v39, v69, v73
	v_fma_f32 v73, -v40, v70, v73
	v_fma_f32 v73, -v41, v71, v73
	s_waitcnt lgkmcnt(2)
	v_fma_f32 v73, -v42, v72, v73
	ds_read_b128 v[38:41], v62 offset:6320
	ds_read_b128 v[42:45], v62 offset:6336
	s_waitcnt lgkmcnt(3)
	v_fma_f32 v74, -v20, v68, v74
	v_fma_f32 v74, -v21, v69, v74
	v_fma_f32 v74, -v22, v70, v74
	v_fma_f32 v74, -v23, v71, v74
	s_waitcnt lgkmcnt(2)
	v_fma_f32 v74, -v24, v72, v74
	v_fma_f32 v74, -v25, v73, v74
	ds_read_b128 v[20:23], v62 offset:6592
	ds_read_b128 v[24:27], v62 offset:6608
	s_waitcnt lgkmcnt(3)
	v_fma_f32 v75, -v38, v68, v75
	v_fma_f32 v75, -v39, v69, v75
	v_fma_f32 v75, -v40, v70, v75
	v_fma_f32 v75, -v41, v71, v75
	s_waitcnt lgkmcnt(2)
	v_fma_f32 v75, -v42, v72, v75
	v_fma_f32 v75, -v43, v73, v75
	v_fma_f32 v75, -v44, v74, v75
	ds_read_b128 v[38:41], v62 offset:6864
	ds_read_b128 v[42:45], v62 offset:6880
	ds_read_b128 v[46:49], v62 offset:6896
	s_waitcnt lgkmcnt(4)
	v_fma_f32 v76, -v20, v68, v76
	v_fma_f32 v76, -v21, v69, v76
	v_fma_f32 v76, -v22, v70, v76
	v_fma_f32 v76, -v23, v71, v76
	s_waitcnt lgkmcnt(3)
	v_fma_f32 v76, -v24, v72, v76
	v_fma_f32 v76, -v25, v73, v76
	v_fma_f32 v76, -v26, v74, v76
	v_fma_f32 v76, -v27, v75, v76
	ds_read_b128 v[20:23], v62 offset:7136
	ds_read_b128 v[24:27], v62 offset:7152
	ds_read_b128 v[28:31], v62 offset:7168
	s_waitcnt lgkmcnt(5)
	v_fma_f32 v77, -v38, v68, v77
	v_fma_f32 v77, -v39, v69, v77
	v_fma_f32 v77, -v40, v70, v77
	v_fma_f32 v77, -v41, v71, v77
	s_waitcnt lgkmcnt(4)
	v_fma_f32 v77, -v42, v72, v77
	v_fma_f32 v77, -v43, v73, v77
	v_fma_f32 v77, -v44, v74, v77
	v_fma_f32 v77, -v45, v75, v77
	s_waitcnt lgkmcnt(3)
	v_fma_f32 v77, -v46, v76, v77
	ds_read_b128 v[38:41], v62 offset:7408
	ds_read_b128 v[42:45], v62 offset:7424
	ds_read_b128 v[46:49], v62 offset:7440
	s_waitcnt lgkmcnt(5)
	v_fma_f32 v78, -v20, v68, v78
	v_fma_f32 v78, -v21, v69, v78
	v_fma_f32 v78, -v22, v70, v78
	v_fma_f32 v78, -v23, v71, v78
	s_waitcnt lgkmcnt(4)
	v_fma_f32 v78, -v24, v72, v78
	v_fma_f32 v78, -v25, v73, v78
	v_fma_f32 v78, -v26, v74, v78
	v_fma_f32 v78, -v27, v75, v78
	s_waitcnt lgkmcnt(3)
	v_fma_f32 v78, -v28, v76, v78
	v_fma_f32 v78, -v29, v77, v78
	ds_read_b128 v[20:23], v62 offset:7680
	ds_read_b128 v[24:27], v62 offset:7696
	ds_read_b128 v[28:31], v62 offset:7712
	s_waitcnt lgkmcnt(5)
	v_fma_f32 v79, -v38, v68, v79
	v_fma_f32 v79, -v39, v69, v79
	v_fma_f32 v79, -v40, v70, v79
	v_fma_f32 v79, -v41, v71, v79
	s_waitcnt lgkmcnt(4)
	v_fma_f32 v79, -v42, v72, v79
	v_fma_f32 v79, -v43, v73, v79
	v_fma_f32 v79, -v44, v74, v79
	v_fma_f32 v79, -v45, v75, v79
	s_waitcnt lgkmcnt(3)
	v_fma_f32 v79, -v46, v76, v79
	v_fma_f32 v79, -v47, v77, v79
	v_fma_f32 v79, -v48, v78, v79
	ds_read_b128 v[38:41], v62 offset:7952
	ds_read_b128 v[42:45], v62 offset:7968
	ds_read_b128 v[46:49], v62 offset:7984
	ds_read_b128 v[50:53], v62 offset:8000
	s_waitcnt lgkmcnt(6)
	v_fma_f32 v80, -v20, v68, v80
	v_fma_f32 v80, -v21, v69, v80
	v_fma_f32 v80, -v22, v70, v80
	v_fma_f32 v80, -v23, v71, v80
	s_waitcnt lgkmcnt(5)
	v_fma_f32 v80, -v24, v72, v80
	v_fma_f32 v80, -v25, v73, v80
	v_fma_f32 v80, -v26, v74, v80
	v_fma_f32 v80, -v27, v75, v80
	s_waitcnt lgkmcnt(4)
	v_fma_f32 v80, -v28, v76, v80
	v_fma_f32 v80, -v29, v77, v80
	v_fma_f32 v80, -v30, v78, v80
	v_fma_f32 v80, -v31, v79, v80
	ds_read_b128 v[20:23], v62 offset:8224
	ds_read_b128 v[24:27], v62 offset:8240
	ds_read_b128 v[28:31], v62 offset:8256
	ds_read_b128 v[32:35], v62 offset:8272
	s_waitcnt lgkmcnt(7)
	v_fma_f32 v81, -v38, v68, v81
	v_fma_f32 v81, -v39, v69, v81
	v_fma_f32 v81, -v40, v70, v81
	v_fma_f32 v81, -v41, v71, v81
	s_waitcnt lgkmcnt(6)
	v_fma_f32 v81, -v42, v72, v81
	v_fma_f32 v81, -v43, v73, v81
	v_fma_f32 v81, -v44, v74, v81
	v_fma_f32 v81, -v45, v75, v81
	s_waitcnt lgkmcnt(5)
	v_fma_f32 v81, -v46, v76, v81
	v_fma_f32 v81, -v47, v77, v81
	v_fma_f32 v81, -v48, v78, v81
	v_fma_f32 v81, -v49, v79, v81
	s_waitcnt lgkmcnt(4)
	v_fma_f32 v81, -v50, v80, v81
	ds_read_b128 v[38:41], v62 offset:8496
	ds_read_b128 v[42:45], v62 offset:8512
	ds_read_b128 v[46:49], v62 offset:8528
	ds_read_b128 v[50:53], v62 offset:8544
	s_waitcnt lgkmcnt(7)
	v_fma_f32 v82, -v20, v68, v82
	v_fma_f32 v82, -v21, v69, v82
	v_fma_f32 v82, -v22, v70, v82
	v_fma_f32 v82, -v23, v71, v82
	s_waitcnt lgkmcnt(6)
	v_fma_f32 v82, -v24, v72, v82
	v_fma_f32 v82, -v25, v73, v82
	v_fma_f32 v82, -v26, v74, v82
	v_fma_f32 v82, -v27, v75, v82
	s_waitcnt lgkmcnt(5)
	v_fma_f32 v82, -v28, v76, v82
	v_fma_f32 v82, -v29, v77, v82
	v_fma_f32 v82, -v30, v78, v82
	v_fma_f32 v82, -v31, v79, v82
	s_waitcnt lgkmcnt(4)
	v_fma_f32 v82, -v32, v80, v82
	v_fma_f32 v82, -v33, v81, v82
	s_waitcnt lgkmcnt(3)
	v_fma_f32 v83, -v38, v68, v83
	v_fma_f32 v83, -v39, v69, v83
	v_fma_f32 v83, -v40, v70, v83
	v_fma_f32 v83, -v41, v71, v83
	s_waitcnt lgkmcnt(2)
	v_fma_f32 v83, -v42, v72, v83
	v_fma_f32 v83, -v43, v73, v83
	v_fma_f32 v83, -v44, v74, v83
	v_fma_f32 v83, -v45, v75, v83
	s_waitcnt lgkmcnt(1)
	v_fma_f32 v83, -v46, v76, v83
	v_fma_f32 v83, -v47, v77, v83
	v_fma_f32 v83, -v48, v78, v83
	v_fma_f32 v83, -v49, v79, v83
	s_waitcnt lgkmcnt(0)
	v_fma_f32 v83, -v50, v80, v83
	v_fma_f32 v83, -v51, v81, v83
	v_fma_f32 v83, -v52, v82, v83
	ds_write_b32 v58, v68 offset:16384
	ds_write_b32 v58, v69 offset:17408
	ds_write_b32 v58, v70 offset:18432
	ds_write_b32 v58, v71 offset:19456
	ds_write_b32 v58, v72 offset:20480
	ds_write_b32 v58, v73 offset:21504
	ds_write_b32 v58, v74 offset:22528
	ds_write_b32 v58, v75 offset:23552
	ds_write_b32 v58, v76 offset:24576
	ds_write_b32 v58, v77 offset:25600
	ds_write_b32 v58, v78 offset:26624
	ds_write_b32 v58, v79 offset:27648
	ds_write_b32 v58, v80 offset:28672
	ds_write_b32 v58, v81 offset:29696
	ds_write_b32 v58, v82 offset:30720
	ds_write_b32 v58, v83 offset:31744
	v_add_u32 v64, 0x4000, v61
	v_cvt_pk_bf16_f32 v2, v68, v68
	global_store_short v64, v2, s[36:37] offset:0
	v_cvt_pk_bf16_f32 v3, v69, v69
	global_store_short v64, v3, s[36:37] offset:1024
	v_cvt_pk_bf16_f32 v4, v70, v70
	global_store_short v64, v4, s[36:37] offset:2048
	v_cvt_pk_bf16_f32 v5, v71, v71
	global_store_short v64, v5, s[36:37] offset:3072
	v_add_u32 v64, 0x5000, v61
	v_cvt_pk_bf16_f32 v6, v72, v72
	global_store_short v64, v6, s[36:37] offset:0
	v_cvt_pk_bf16_f32 v7, v73, v73
	global_store_short v64, v7, s[36:37] offset:1024
	v_cvt_pk_bf16_f32 v8, v74, v74
	global_store_short v64, v8, s[36:37] offset:2048
	v_cvt_pk_bf16_f32 v9, v75, v75
	global_store_short v64, v9, s[36:37] offset:3072
	v_add_u32 v64, 0x6000, v61
	v_cvt_pk_bf16_f32 v2, v76, v76
	global_store_short v64, v2, s[36:37] offset:0
	v_cvt_pk_bf16_f32 v3, v77, v77
	global_store_short v64, v3, s[36:37] offset:1024
	v_cvt_pk_bf16_f32 v4, v78, v78
	global_store_short v64, v4, s[36:37] offset:2048
	v_cvt_pk_bf16_f32 v5, v79, v79
	global_store_short v64, v5, s[36:37] offset:3072
	v_add_u32 v64, 0x7000, v61
	v_cvt_pk_bf16_f32 v6, v80, v80
	global_store_short v64, v6, s[36:37] offset:0
	v_cvt_pk_bf16_f32 v7, v81, v81
	global_store_short v64, v7, s[36:37] offset:1024
	v_cvt_pk_bf16_f32 v8, v82, v82
	global_store_short v64, v8, s[36:37] offset:2048
	v_cvt_pk_bf16_f32 v9, v83, v83
	global_store_short v64, v9, s[36:37] offset:3072
	ds_read_b32 v36, v54 offset:8704
	ds_read_b32 v38, v55 offset:0
	ds_read_b32 v39, v55 offset:64
	ds_read_b32 v40, v55 offset:128
	ds_read_b32 v41, v55 offset:192
	ds_read_b32 v19, v54 offset:8720
	ds_read_b32 v42, v55 offset:4096
	ds_read_b32 v43, v55 offset:4160
	ds_read_b32 v44, v55 offset:4224
	ds_read_b32 v45, v55 offset:4288
	s_waitcnt lgkmcnt(8)
	v_mfma_f32_16x16x4_f32 v[20:23], v36, v38, 0
	s_waitcnt lgkmcnt(7)
	v_mfma_f32_16x16x4_f32 v[24:27], v36, v39, 0
	s_waitcnt lgkmcnt(6)
	v_mfma_f32_16x16x4_f32 v[28:31], v36, v40, 0
	s_waitcnt lgkmcnt(5)
	v_mfma_f32_16x16x4_f32 v[32:35], v36, v41, 0
	ds_read_b32 v36, v54 offset:8736
	ds_read_b32 v38, v55 offset:8192
	ds_read_b32 v39, v55 offset:8256
	ds_read_b32 v40, v55 offset:8320
	ds_read_b32 v41, v55 offset:8384
	s_waitcnt lgkmcnt(8)
	v_mfma_f32_16x16x4_f32 v[20:23], v19, v42, v[20:23]
	s_waitcnt lgkmcnt(7)
	v_mfma_f32_16x16x4_f32 v[24:27], v19, v43, v[24:27]
	s_waitcnt lgkmcnt(6)
	v_mfma_f32_16x16x4_f32 v[28:31], v19, v44, v[28:31]
	s_waitcnt lgkmcnt(5)
	v_mfma_f32_16x16x4_f32 v[32:35], v19, v45, v[32:35]
	ds_read_b32 v19, v54 offset:8752
	ds_read_b32 v42, v55 offset:12288
	ds_read_b32 v43, v55 offset:12352
	ds_read_b32 v44, v55 offset:12416
	ds_read_b32 v45, v55 offset:12480
	s_waitcnt lgkmcnt(8)
	v_mfma_f32_16x16x4_f32 v[20:23], v36, v38, v[20:23]
	s_waitcnt lgkmcnt(7)
	v_mfma_f32_16x16x4_f32 v[24:27], v36, v39, v[24:27]
	s_waitcnt lgkmcnt(6)
	v_mfma_f32_16x16x4_f32 v[28:31], v36, v40, v[28:31]
	s_waitcnt lgkmcnt(5)
	v_mfma_f32_16x16x4_f32 v[32:35], v36, v41, v[32:35]
	ds_read_b32 v36, v54 offset:8768
	ds_read_b32 v38, v55 offset:16384
	ds_read_b32 v39, v55 offset:16448
	ds_read_b32 v40, v55 offset:16512
	ds_read_b32 v41, v55 offset:16576
	s_waitcnt lgkmcnt(8)
	v_mfma_f32_16x16x4_f32 v[20:23], v19, v42, v[20:23]
	s_waitcnt lgkmcnt(7)
	v_mfma_f32_16x16x4_f32 v[24:27], v19, v43, v[24:27]
	s_waitcnt lgkmcnt(6)
	v_mfma_f32_16x16x4_f32 v[28:31], v19, v44, v[28:31]
	s_waitcnt lgkmcnt(5)
	v_mfma_f32_16x16x4_f32 v[32:35], v19, v45, v[32:35]
	ds_read_b32 v19, v54 offset:8784
	ds_read_b32 v42, v55 offset:20480
	ds_read_b32 v43, v55 offset:20544
	ds_read_b32 v44, v55 offset:20608
	ds_read_b32 v45, v55 offset:20672
	s_waitcnt lgkmcnt(8)
	v_mfma_f32_16x16x4_f32 v[20:23], v36, v38, v[20:23]
	s_waitcnt lgkmcnt(7)
	v_mfma_f32_16x16x4_f32 v[24:27], v36, v39, v[24:27]
	s_waitcnt lgkmcnt(6)
	v_mfma_f32_16x16x4_f32 v[28:31], v36, v40, v[28:31]
	s_waitcnt lgkmcnt(5)
	v_mfma_f32_16x16x4_f32 v[32:35], v36, v41, v[32:35]
	ds_read_b32 v36, v54 offset:8800
	ds_read_b32 v38, v55 offset:24576
	ds_read_b32 v39, v55 offset:24640
	ds_read_b32 v40, v55 offset:24704
	ds_read_b32 v41, v55 offset:24768
	s_waitcnt lgkmcnt(8)
	v_mfma_f32_16x16x4_f32 v[20:23], v19, v42, v[20:23]
	s_waitcnt lgkmcnt(7)
	v_mfma_f32_16x16x4_f32 v[24:27], v19, v43, v[24:27]
	s_waitcnt lgkmcnt(6)
	v_mfma_f32_16x16x4_f32 v[28:31], v19, v44, v[28:31]
	s_waitcnt lgkmcnt(5)
	v_mfma_f32_16x16x4_f32 v[32:35], v19, v45, v[32:35]
	ds_read_b32 v19, v54 offset:8816
	ds_read_b32 v42, v55 offset:28672
	ds_read_b32 v43, v55 offset:28736
	ds_read_b32 v44, v55 offset:28800
	ds_read_b32 v45, v55 offset:28864
	s_waitcnt lgkmcnt(8)
	v_mfma_f32_16x16x4_f32 v[20:23], v36, v38, v[20:23]
	s_waitcnt lgkmcnt(7)
	v_mfma_f32_16x16x4_f32 v[24:27], v36, v39, v[24:27]
	s_waitcnt lgkmcnt(6)
	v_mfma_f32_16x16x4_f32 v[28:31], v36, v40, v[28:31]
	s_waitcnt lgkmcnt(5)
	v_mfma_f32_16x16x4_f32 v[32:35], v36, v41, v[32:35]
	s_waitcnt lgkmcnt(3)
	v_mfma_f32_16x16x4_f32 v[20:23], v19, v42, v[20:23]
	s_waitcnt lgkmcnt(2)
	v_mfma_f32_16x16x4_f32 v[24:27], v19, v43, v[24:27]
	s_waitcnt lgkmcnt(1)
	v_mfma_f32_16x16x4_f32 v[28:31], v19, v44, v[28:31]
	s_waitcnt lgkmcnt(0)
	v_mfma_f32_16x16x4_f32 v[32:35], v19, v45, v[32:35]
	s_nop 5
	ds_write_b128 v56, v[20:23] offset:0
	s_nop 0
	ds_write_b128 v56, v[24:27] offset:1280
	s_nop 0
	ds_write_b128 v56, v[28:31] offset:2560
	s_nop 0
	ds_write_b128 v56, v[32:35] offset:3840
	ds_read_b128 v[2:5], v57 offset:0
	ds_read_b128 v[6:9], v57 offset:16
	ds_read_b128 v[10:13], v57 offset:32
	ds_read_b128 v[14:17], v57 offset:48
	ds_read_b128 v[38:41], v62 offset:17792
	ds_read_b128 v[42:45], v62 offset:17808
	ds_read_b128 v[46:49], v62 offset:17824
	ds_read_b128 v[50:53], v62 offset:17840
	ds_read_u16 v68, v59 offset:8704
	ds_read_u16 v69, v59 offset:8976
	ds_read_u16 v70, v59 offset:9248
	ds_read_u16 v71, v59 offset:9520
	ds_read_u16 v72, v59 offset:9792
	ds_read_u16 v73, v59 offset:10064
	ds_read_u16 v74, v59 offset:10336
	ds_read_u16 v75, v59 offset:10608
	ds_read_u16 v76, v59 offset:10880
	ds_read_u16 v77, v59 offset:11152
	ds_read_u16 v78, v59 offset:11424
	ds_read_u16 v79, v59 offset:11696
	ds_read_u16 v80, v59 offset:11968
	ds_read_u16 v81, v59 offset:12240
	ds_read_u16 v82, v59 offset:12512
	ds_read_u16 v83, v59 offset:12784
	ds_read_b128 v[20:23], v62 offset:19328
	ds_read_b128 v[24:27], v62 offset:19344
	ds_read_b128 v[28:31], v62 offset:19360
	ds_read_b128 v[32:35], v62 offset:19376
	s_waitcnt lgkmcnt(15)
	v_lshlrev_b32 v68, 16, v68
	s_waitcnt lgkmcnt(15)
	v_lshlrev_b32 v69, 16, v69
	s_waitcnt lgkmcnt(15)
	v_lshlrev_b32 v70, 16, v70
	s_waitcnt lgkmcnt(15)
	v_lshlrev_b32 v71, 16, v71
	s_waitcnt lgkmcnt(15)
	v_lshlrev_b32 v72, 16, v72
	s_waitcnt lgkmcnt(14)
	v_lshlrev_b32 v73, 16, v73
	s_waitcnt lgkmcnt(13)
	v_lshlrev_b32 v74, 16, v74
	s_waitcnt lgkmcnt(12)
	v_lshlrev_b32 v75, 16, v75
	s_waitcnt lgkmcnt(11)
	v_lshlrev_b32 v76, 16, v76
	s_waitcnt lgkmcnt(10)
	v_lshlrev_b32 v77, 16, v77
	s_waitcnt lgkmcnt(9)
	v_lshlrev_b32 v78, 16, v78
	s_waitcnt lgkmcnt(8)
	v_lshlrev_b32 v79, 16, v79
	s_waitcnt lgkmcnt(7)
	v_lshlrev_b32 v80, 16, v80
	s_waitcnt lgkmcnt(6)
	v_lshlrev_b32 v81, 16, v81
	s_waitcnt lgkmcnt(5)
	v_lshlrev_b32 v82, 16, v82
	s_waitcnt lgkmcnt(4)
	v_lshlrev_b32 v83, 16, v83
	s_waitcnt lgkmcnt(3)
	v_mul_f32 v68, v68, v20
	v_mul_f32 v69, v69, v21
	v_mul_f32 v70, v70, v22
	v_mul_f32 v71, v71, v23
	s_waitcnt lgkmcnt(2)
	v_mul_f32 v72, v72, v24
	v_mul_f32 v73, v73, v25
	v_mul_f32 v74, v74, v26
	v_mul_f32 v75, v75, v27
	s_waitcnt lgkmcnt(1)
	v_mul_f32 v76, v76, v28
	v_mul_f32 v77, v77, v29
	v_mul_f32 v78, v78, v30
	v_mul_f32 v79, v79, v31
	s_waitcnt lgkmcnt(0)
	v_mul_f32 v80, v80, v32
	v_mul_f32 v81, v81, v33
	v_mul_f32 v82, v82, v34
	v_mul_f32 v83, v83, v35
	ds_read_b128 v[20:23], v62 offset:19584
	ds_read_b128 v[24:27], v62 offset:19600
	ds_read_b128 v[28:31], v62 offset:19616
	ds_read_b128 v[32:35], v62 offset:19632
	v_mul_f32 v68, v68, v38
	v_mul_f32 v69, v69, v39
	v_mul_f32 v70, v70, v40
	v_mul_f32 v71, v71, v41
	v_mul_f32 v72, v72, v42
	v_mul_f32 v73, v73, v43
	v_mul_f32 v74, v74, v44
	v_mul_f32 v75, v75, v45
	v_mul_f32 v76, v76, v46
	v_mul_f32 v77, v77, v47
	v_mul_f32 v78, v78, v48
	v_mul_f32 v79, v79, v49
	v_mul_f32 v80, v80, v50
	v_mul_f32 v81, v81, v51
	v_mul_f32 v82, v82, v52
	v_mul_f32 v83, v83, v53
	s_waitcnt lgkmcnt(3)
	v_fma_f32 v68, v68, v20, -v2
	v_fma_f32 v69, v69, v21, -v3
	v_fma_f32 v70, v70, v22, -v4
	v_fma_f32 v71, v71, v23, -v5
	s_waitcnt lgkmcnt(2)
	v_fma_f32 v72, v72, v24, -v6
	v_fma_f32 v73, v73, v25, -v7
	v_fma_f32 v74, v74, v26, -v8
	v_fma_f32 v75, v75, v27, -v9
	s_waitcnt lgkmcnt(1)
	v_fma_f32 v76, v76, v28, -v10
	v_fma_f32 v77, v77, v29, -v11
	v_fma_f32 v78, v78, v30, -v12
	v_fma_f32 v79, v79, v31, -v13
	s_waitcnt lgkmcnt(0)
	v_fma_f32 v80, v80, v32, -v14
	v_fma_f32 v81, v81, v33, -v15
	v_fma_f32 v82, v82, v34, -v16
	v_fma_f32 v83, v83, v35, -v17
	ds_read_b128 v[38:41], v62 offset:9104
	ds_read_b128 v[20:23], v62 offset:9376
	s_waitcnt lgkmcnt(1)
	v_fma_f32 v69, -v38, v68, v69
	ds_read_b128 v[38:41], v62 offset:9648
	s_waitcnt lgkmcnt(1)
	v_fma_f32 v70, -v20, v68, v70
	v_fma_f32 v70, -v21, v69, v70
	ds_read_b128 v[20:23], v62 offset:9920
	s_waitcnt lgkmcnt(1)
	v_fma_f32 v71, -v38, v68, v71
	v_fma_f32 v71, -v39, v69, v71
	v_fma_f32 v71, -v40, v70, v71
	ds_read_b128 v[38:41], v62 offset:10192
	ds_read_b128 v[42:45], v62 offset:10208
	s_waitcnt lgkmcnt(2)
	v_fma_f32 v72, -v20, v68, v72
	v_fma_f32 v72, -v21, v69, v72
	v_fma_f32 v72, -v22, v70, v72
	v_fma_f32 v72, -v23, v71, v72
	ds_read_b128 v[20:23], v62 offset:10464
	ds_read_b128 v[24:27], v62 offset:10480
	s_waitcnt lgkmcnt(3)
	v_fma_f32 v73, -v38, v68, v73
	v_fma_f32 v73, -v39, v69, v73
	v_fma_f32 v73, -v40, v70, v73
	v_fma_f32 v73, -v41, v71, v73
	s_waitcnt lgkmcnt(2)
	v_fma_f32 v73, -v42, v72, v73
	ds_read_b128 v[38:41], v62 offset:10736
	ds_read_b128 v[42:45], v62 offset:10752
	s_waitcnt lgkmcnt(3)
	v_fma_f32 v74, -v20, v68, v74
	v_fma_f32 v74, -v21, v69, v74
	v_fma_f32 v74, -v22, v70, v74
	v_fma_f32 v74, -v23, v71, v74
	s_waitcnt lgkmcnt(2)
	v_fma_f32 v74, -v24, v72, v74
	v_fma_f32 v74, -v25, v73, v74
	ds_read_b128 v[20:23], v62 offset:11008
	ds_read_b128 v[24:27], v62 offset:11024
	s_waitcnt lgkmcnt(3)
	v_fma_f32 v75, -v38, v68, v75
	v_fma_f32 v75, -v39, v69, v75
	v_fma_f32 v75, -v40, v70, v75
	v_fma_f32 v75, -v41, v71, v75
	s_waitcnt lgkmcnt(2)
	v_fma_f32 v75, -v42, v72, v75
	v_fma_f32 v75, -v43, v73, v75
	v_fma_f32 v75, -v44, v74, v75
	ds_read_b128 v[38:41], v62 offset:11280
	ds_read_b128 v[42:45], v62 offset:11296
	ds_read_b128 v[46:49], v62 offset:11312
	s_waitcnt lgkmcnt(4)
	v_fma_f32 v76, -v20, v68, v76
	v_fma_f32 v76, -v21, v69, v76
	v_fma_f32 v76, -v22, v70, v76
	v_fma_f32 v76, -v23, v71, v76
	s_waitcnt lgkmcnt(3)
	v_fma_f32 v76, -v24, v72, v76
	v_fma_f32 v76, -v25, v73, v76
	v_fma_f32 v76, -v26, v74, v76
	v_fma_f32 v76, -v27, v75, v76
	ds_read_b128 v[20:23], v62 offset:11552
	ds_read_b128 v[24:27], v62 offset:11568
	ds_read_b128 v[28:31], v62 offset:11584
	s_waitcnt lgkmcnt(5)
	v_fma_f32 v77, -v38, v68, v77
	v_fma_f32 v77, -v39, v69, v77
	v_fma_f32 v77, -v40, v70, v77
	v_fma_f32 v77, -v41, v71, v77
	s_waitcnt lgkmcnt(4)
	v_fma_f32 v77, -v42, v72, v77
	v_fma_f32 v77, -v43, v73, v77
	v_fma_f32 v77, -v44, v74, v77
	v_fma_f32 v77, -v45, v75, v77
	s_waitcnt lgkmcnt(3)
	v_fma_f32 v77, -v46, v76, v77
	ds_read_b128 v[38:41], v62 offset:11824
	ds_read_b128 v[42:45], v62 offset:11840
	ds_read_b128 v[46:49], v62 offset:11856
	s_waitcnt lgkmcnt(5)
	v_fma_f32 v78, -v20, v68, v78
	v_fma_f32 v78, -v21, v69, v78
	v_fma_f32 v78, -v22, v70, v78
	v_fma_f32 v78, -v23, v71, v78
	s_waitcnt lgkmcnt(4)
	v_fma_f32 v78, -v24, v72, v78
	v_fma_f32 v78, -v25, v73, v78
	v_fma_f32 v78, -v26, v74, v78
	v_fma_f32 v78, -v27, v75, v78
	s_waitcnt lgkmcnt(3)
	v_fma_f32 v78, -v28, v76, v78
	v_fma_f32 v78, -v29, v77, v78
	ds_read_b128 v[20:23], v62 offset:12096
	ds_read_b128 v[24:27], v62 offset:12112
	ds_read_b128 v[28:31], v62 offset:12128
	s_waitcnt lgkmcnt(5)
	v_fma_f32 v79, -v38, v68, v79
	v_fma_f32 v79, -v39, v69, v79
	v_fma_f32 v79, -v40, v70, v79
	v_fma_f32 v79, -v41, v71, v79
	s_waitcnt lgkmcnt(4)
	v_fma_f32 v79, -v42, v72, v79
	v_fma_f32 v79, -v43, v73, v79
	v_fma_f32 v79, -v44, v74, v79
	v_fma_f32 v79, -v45, v75, v79
	s_waitcnt lgkmcnt(3)
	v_fma_f32 v79, -v46, v76, v79
	v_fma_f32 v79, -v47, v77, v79
	v_fma_f32 v79, -v48, v78, v79
	ds_read_b128 v[38:41], v62 offset:12368
	ds_read_b128 v[42:45], v62 offset:12384
	ds_read_b128 v[46:49], v62 offset:12400
	ds_read_b128 v[50:53], v62 offset:12416
	s_waitcnt lgkmcnt(6)
	v_fma_f32 v80, -v20, v68, v80
	v_fma_f32 v80, -v21, v69, v80
	v_fma_f32 v80, -v22, v70, v80
	v_fma_f32 v80, -v23, v71, v80
	s_waitcnt lgkmcnt(5)
	v_fma_f32 v80, -v24, v72, v80
	v_fma_f32 v80, -v25, v73, v80
	v_fma_f32 v80, -v26, v74, v80
	v_fma_f32 v80, -v27, v75, v80
	s_waitcnt lgkmcnt(4)
	v_fma_f32 v80, -v28, v76, v80
	v_fma_f32 v80, -v29, v77, v80
	v_fma_f32 v80, -v30, v78, v80
	v_fma_f32 v80, -v31, v79, v80
	ds_read_b128 v[20:23], v62 offset:12640
	ds_read_b128 v[24:27], v62 offset:12656
	ds_read_b128 v[28:31], v62 offset:12672
	ds_read_b128 v[32:35], v62 offset:12688
	s_waitcnt lgkmcnt(7)
	v_fma_f32 v81, -v38, v68, v81
	v_fma_f32 v81, -v39, v69, v81
	v_fma_f32 v81, -v40, v70, v81
	v_fma_f32 v81, -v41, v71, v81
	s_waitcnt lgkmcnt(6)
	v_fma_f32 v81, -v42, v72, v81
	v_fma_f32 v81, -v43, v73, v81
	v_fma_f32 v81, -v44, v74, v81
	v_fma_f32 v81, -v45, v75, v81
	s_waitcnt lgkmcnt(5)
	v_fma_f32 v81, -v46, v76, v81
	v_fma_f32 v81, -v47, v77, v81
	v_fma_f32 v81, -v48, v78, v81
	v_fma_f32 v81, -v49, v79, v81
	s_waitcnt lgkmcnt(4)
	v_fma_f32 v81, -v50, v80, v81
	ds_read_b128 v[38:41], v62 offset:12912
	ds_read_b128 v[42:45], v62 offset:12928
	ds_read_b128 v[46:49], v62 offset:12944
	ds_read_b128 v[50:53], v62 offset:12960
	s_waitcnt lgkmcnt(7)
	v_fma_f32 v82, -v20, v68, v82
	v_fma_f32 v82, -v21, v69, v82
	v_fma_f32 v82, -v22, v70, v82
	v_fma_f32 v82, -v23, v71, v82
	s_waitcnt lgkmcnt(6)
	v_fma_f32 v82, -v24, v72, v82
	v_fma_f32 v82, -v25, v73, v82
	v_fma_f32 v82, -v26, v74, v82
	v_fma_f32 v82, -v27, v75, v82
	s_waitcnt lgkmcnt(5)
	v_fma_f32 v82, -v28, v76, v82
	v_fma_f32 v82, -v29, v77, v82
	v_fma_f32 v82, -v30, v78, v82
	v_fma_f32 v82, -v31, v79, v82
	s_waitcnt lgkmcnt(4)
	v_fma_f32 v82, -v32, v80, v82
	v_fma_f32 v82, -v33, v81, v82
	s_waitcnt lgkmcnt(3)
	v_fma_f32 v83, -v38, v68, v83
	v_fma_f32 v83, -v39, v69, v83
	v_fma_f32 v83, -v40, v70, v83
	v_fma_f32 v83, -v41, v71, v83
	s_waitcnt lgkmcnt(2)
	v_fma_f32 v83, -v42, v72, v83
	v_fma_f32 v83, -v43, v73, v83
	v_fma_f32 v83, -v44, v74, v83
	v_fma_f32 v83, -v45, v75, v83
	s_waitcnt lgkmcnt(1)
	v_fma_f32 v83, -v46, v76, v83
	v_fma_f32 v83, -v47, v77, v83
	v_fma_f32 v83, -v48, v78, v83
	v_fma_f32 v83, -v49, v79, v83
	s_waitcnt lgkmcnt(0)
	v_fma_f32 v83, -v50, v80, v83
	v_fma_f32 v83, -v51, v81, v83
	v_fma_f32 v83, -v52, v82, v83
	ds_write_b32 v58, v68 offset:32768
	ds_write_b32 v58, v69 offset:33792
	ds_write_b32 v58, v70 offset:34816
	ds_write_b32 v58, v71 offset:35840
	ds_write_b32 v58, v72 offset:36864
	ds_write_b32 v58, v73 offset:37888
	ds_write_b32 v58, v74 offset:38912
	ds_write_b32 v58, v75 offset:39936
	ds_write_b32 v58, v76 offset:40960
	ds_write_b32 v58, v77 offset:41984
	ds_write_b32 v58, v78 offset:43008
	ds_write_b32 v58, v79 offset:44032
	ds_write_b32 v58, v80 offset:45056
	ds_write_b32 v58, v81 offset:46080
	ds_write_b32 v58, v82 offset:47104
	ds_write_b32 v58, v83 offset:48128
	v_add_u32 v64, 0x8000, v61
	v_cvt_pk_bf16_f32 v2, v68, v68
	global_store_short v64, v2, s[36:37] offset:0
	v_cvt_pk_bf16_f32 v3, v69, v69
	global_store_short v64, v3, s[36:37] offset:1024
	v_cvt_pk_bf16_f32 v4, v70, v70
	global_store_short v64, v4, s[36:37] offset:2048
	v_cvt_pk_bf16_f32 v5, v71, v71
	global_store_short v64, v5, s[36:37] offset:3072
	v_add_u32 v64, 0x9000, v61
	v_cvt_pk_bf16_f32 v6, v72, v72
	global_store_short v64, v6, s[36:37] offset:0
	v_cvt_pk_bf16_f32 v7, v73, v73
	global_store_short v64, v7, s[36:37] offset:1024
	v_cvt_pk_bf16_f32 v8, v74, v74
	global_store_short v64, v8, s[36:37] offset:2048
	v_cvt_pk_bf16_f32 v9, v75, v75
	global_store_short v64, v9, s[36:37] offset:3072
	v_add_u32 v64, 0xa000, v61
	v_cvt_pk_bf16_f32 v2, v76, v76
	global_store_short v64, v2, s[36:37] offset:0
	v_cvt_pk_bf16_f32 v3, v77, v77
	global_store_short v64, v3, s[36:37] offset:1024
	v_cvt_pk_bf16_f32 v4, v78, v78
	global_store_short v64, v4, s[36:37] offset:2048
	v_cvt_pk_bf16_f32 v5, v79, v79
	global_store_short v64, v5, s[36:37] offset:3072
	v_add_u32 v64, 0xb000, v61
	v_cvt_pk_bf16_f32 v6, v80, v80
	global_store_short v64, v6, s[36:37] offset:0
	v_cvt_pk_bf16_f32 v7, v81, v81
	global_store_short v64, v7, s[36:37] offset:1024
	v_cvt_pk_bf16_f32 v8, v82, v82
	global_store_short v64, v8, s[36:37] offset:2048
	v_cvt_pk_bf16_f32 v9, v83, v83
	global_store_short v64, v9, s[36:37] offset:3072
	ds_read_b32 v36, v54 offset:13056
	ds_read_b32 v38, v55 offset:0
	ds_read_b32 v39, v55 offset:64
	ds_read_b32 v40, v55 offset:128
	ds_read_b32 v41, v55 offset:192
	ds_read_b32 v19, v54 offset:13072
	ds_read_b32 v42, v55 offset:4096
	ds_read_b32 v43, v55 offset:4160
	ds_read_b32 v44, v55 offset:4224
	ds_read_b32 v45, v55 offset:4288
	s_waitcnt lgkmcnt(8)
	v_mfma_f32_16x16x4_f32 v[20:23], v36, v38, 0
	s_waitcnt lgkmcnt(7)
	v_mfma_f32_16x16x4_f32 v[24:27], v36, v39, 0
	s_waitcnt lgkmcnt(6)
	v_mfma_f32_16x16x4_f32 v[28:31], v36, v40, 0
	s_waitcnt lgkmcnt(5)
	v_mfma_f32_16x16x4_f32 v[32:35], v36, v41, 0
	ds_read_b32 v36, v54 offset:13088
	ds_read_b32 v38, v55 offset:8192
	ds_read_b32 v39, v55 offset:8256
	ds_read_b32 v40, v55 offset:8320
	ds_read_b32 v41, v55 offset:8384
	s_waitcnt lgkmcnt(8)
	v_mfma_f32_16x16x4_f32 v[20:23], v19, v42, v[20:23]
	s_waitcnt lgkmcnt(7)
	v_mfma_f32_16x16x4_f32 v[24:27], v19, v43, v[24:27]
	s_waitcnt lgkmcnt(6)
	v_mfma_f32_16x16x4_f32 v[28:31], v19, v44, v[28:31]
	s_waitcnt lgkmcnt(5)
	v_mfma_f32_16x16x4_f32 v[32:35], v19, v45, v[32:35]
	ds_read_b32 v19, v54 offset:13104
	ds_read_b32 v42, v55 offset:12288
	ds_read_b32 v43, v55 offset:12352
	ds_read_b32 v44, v55 offset:12416
	ds_read_b32 v45, v55 offset:12480
	s_waitcnt lgkmcnt(8)
	v_mfma_f32_16x16x4_f32 v[20:23], v36, v38, v[20:23]
	s_waitcnt lgkmcnt(7)
	v_mfma_f32_16x16x4_f32 v[24:27], v36, v39, v[24:27]
	s_waitcnt lgkmcnt(6)
	v_mfma_f32_16x16x4_f32 v[28:31], v36, v40, v[28:31]
	s_waitcnt lgkmcnt(5)
	v_mfma_f32_16x16x4_f32 v[32:35], v36, v41, v[32:35]
	ds_read_b32 v36, v54 offset:13120
	ds_read_b32 v38, v55 offset:16384
	ds_read_b32 v39, v55 offset:16448
	ds_read_b32 v40, v55 offset:16512
	ds_read_b32 v41, v55 offset:16576
	s_waitcnt lgkmcnt(8)
	v_mfma_f32_16x16x4_f32 v[20:23], v19, v42, v[20:23]
	s_waitcnt lgkmcnt(7)
	v_mfma_f32_16x16x4_f32 v[24:27], v19, v43, v[24:27]
	s_waitcnt lgkmcnt(6)
	v_mfma_f32_16x16x4_f32 v[28:31], v19, v44, v[28:31]
	s_waitcnt lgkmcnt(5)
	v_mfma_f32_16x16x4_f32 v[32:35], v19, v45, v[32:35]
	ds_read_b32 v19, v54 offset:13136
	ds_read_b32 v42, v55 offset:20480
	ds_read_b32 v43, v55 offset:20544
	ds_read_b32 v44, v55 offset:20608
	ds_read_b32 v45, v55 offset:20672
	s_waitcnt lgkmcnt(8)
	v_mfma_f32_16x16x4_f32 v[20:23], v36, v38, v[20:23]
	s_waitcnt lgkmcnt(7)
	v_mfma_f32_16x16x4_f32 v[24:27], v36, v39, v[24:27]
	s_waitcnt lgkmcnt(6)
	v_mfma_f32_16x16x4_f32 v[28:31], v36, v40, v[28:31]
	s_waitcnt lgkmcnt(5)
	v_mfma_f32_16x16x4_f32 v[32:35], v36, v41, v[32:35]
	ds_read_b32 v36, v54 offset:13152
	ds_read_b32 v38, v55 offset:24576
	ds_read_b32 v39, v55 offset:24640
	ds_read_b32 v40, v55 offset:24704
	ds_read_b32 v41, v55 offset:24768
	s_waitcnt lgkmcnt(8)
	v_mfma_f32_16x16x4_f32 v[20:23], v19, v42, v[20:23]
	s_waitcnt lgkmcnt(7)
	v_mfma_f32_16x16x4_f32 v[24:27], v19, v43, v[24:27]
	s_waitcnt lgkmcnt(6)
	v_mfma_f32_16x16x4_f32 v[28:31], v19, v44, v[28:31]
	s_waitcnt lgkmcnt(5)
	v_mfma_f32_16x16x4_f32 v[32:35], v19, v45, v[32:35]
	ds_read_b32 v19, v54 offset:13168
	ds_read_b32 v42, v55 offset:28672
	ds_read_b32 v43, v55 offset:28736
	ds_read_b32 v44, v55 offset:28800
	ds_read_b32 v45, v55 offset:28864
	s_waitcnt lgkmcnt(8)
	v_mfma_f32_16x16x4_f32 v[20:23], v36, v38, v[20:23]
	s_waitcnt lgkmcnt(7)
	v_mfma_f32_16x16x4_f32 v[24:27], v36, v39, v[24:27]
	s_waitcnt lgkmcnt(6)
	v_mfma_f32_16x16x4_f32 v[28:31], v36, v40, v[28:31]
	s_waitcnt lgkmcnt(5)
	v_mfma_f32_16x16x4_f32 v[32:35], v36, v41, v[32:35]
	ds_read_b32 v36, v54 offset:13184
	ds_read_b32 v38, v55 offset:32768
	ds_read_b32 v39, v55 offset:32832
	ds_read_b32 v40, v55 offset:32896
	ds_read_b32 v41, v55 offset:32960
	s_waitcnt lgkmcnt(8)
	v_mfma_f32_16x16x4_f32 v[20:23], v19, v42, v[20:23]
	s_waitcnt lgkmcnt(7)
	v_mfma_f32_16x16x4_f32 v[24:27], v19, v43, v[24:27]
	s_waitcnt lgkmcnt(6)
	v_mfma_f32_16x16x4_f32 v[28:31], v19, v44, v[28:31]
	s_waitcnt lgkmcnt(5)
	v_mfma_f32_16x16x4_f32 v[32:35], v19, v45, v[32:35]
	ds_read_b32 v19, v54 offset:13200
	ds_read_b32 v42, v55 offset:36864
	ds_read_b32 v43, v55 offset:36928
	ds_read_b32 v44, v55 offset:36992
	ds_read_b32 v45, v55 offset:37056
	s_waitcnt lgkmcnt(8)
	v_mfma_f32_16x16x4_f32 v[20:23], v36, v38, v[20:23]
	s_waitcnt lgkmcnt(7)
	v_mfma_f32_16x16x4_f32 v[24:27], v36, v39, v[24:27]
	s_waitcnt lgkmcnt(6)
	v_mfma_f32_16x16x4_f32 v[28:31], v36, v40, v[28:31]
	s_waitcnt lgkmcnt(5)
	v_mfma_f32_16x16x4_f32 v[32:35], v36, v41, v[32:35]
	ds_read_b32 v36, v54 offset:13216
	ds_read_b32 v38, v55 offset:40960
	ds_read_b32 v39, v55 offset:41024
	ds_read_b32 v40, v55 offset:41088
	ds_read_b32 v41, v55 offset:41152
	s_waitcnt lgkmcnt(8)
	v_mfma_f32_16x16x4_f32 v[20:23], v19, v42, v[20:23]
	s_waitcnt lgkmcnt(7)
	v_mfma_f32_16x16x4_f32 v[24:27], v19, v43, v[24:27]
	s_waitcnt lgkmcnt(6)
	v_mfma_f32_16x16x4_f32 v[28:31], v19, v44, v[28:31]
	s_waitcnt lgkmcnt(5)
	v_mfma_f32_16x16x4_f32 v[32:35], v19, v45, v[32:35]
	ds_read_b32 v19, v54 offset:13232
	ds_read_b32 v42, v55 offset:45056
	ds_read_b32 v43, v55 offset:45120
	ds_read_b32 v44, v55 offset:45184
	ds_read_b32 v45, v55 offset:45248
	s_waitcnt lgkmcnt(8)
	v_mfma_f32_16x16x4_f32 v[20:23], v36, v38, v[20:23]
	s_waitcnt lgkmcnt(7)
	v_mfma_f32_16x16x4_f32 v[24:27], v36, v39, v[24:27]
	s_waitcnt lgkmcnt(6)
	v_mfma_f32_16x16x4_f32 v[28:31], v36, v40, v[28:31]
	s_waitcnt lgkmcnt(5)
	v_mfma_f32_16x16x4_f32 v[32:35], v36, v41, v[32:35]
	s_waitcnt lgkmcnt(3)
	v_mfma_f32_16x16x4_f32 v[20:23], v19, v42, v[20:23]
	s_waitcnt lgkmcnt(2)
	v_mfma_f32_16x16x4_f32 v[24:27], v19, v43, v[24:27]
	s_waitcnt lgkmcnt(1)
	v_mfma_f32_16x16x4_f32 v[28:31], v19, v44, v[28:31]
	s_waitcnt lgkmcnt(0)
	v_mfma_f32_16x16x4_f32 v[32:35], v19, v45, v[32:35]
	s_nop 5
	ds_write_b128 v56, v[20:23] offset:0
	s_nop 0
	ds_write_b128 v56, v[24:27] offset:1280
	s_nop 0
	ds_write_b128 v56, v[28:31] offset:2560
	s_nop 0
	ds_write_b128 v56, v[32:35] offset:3840
	ds_read_b128 v[2:5], v57 offset:0
	ds_read_b128 v[6:9], v57 offset:16
	ds_read_b128 v[10:13], v57 offset:32
	ds_read_b128 v[14:17], v57 offset:48
	ds_read_b128 v[38:41], v62 offset:17856
	ds_read_b128 v[42:45], v62 offset:17872
	ds_read_b128 v[46:49], v62 offset:17888
	ds_read_b128 v[50:53], v62 offset:17904
	ds_read_u16 v68, v59 offset:13056
	ds_read_u16 v69, v59 offset:13328
	ds_read_u16 v70, v59 offset:13600
	ds_read_u16 v71, v59 offset:13872
	ds_read_u16 v72, v59 offset:14144
	ds_read_u16 v73, v59 offset:14416
	ds_read_u16 v74, v59 offset:14688
	ds_read_u16 v75, v59 offset:14960
	ds_read_u16 v76, v59 offset:15232
	ds_read_u16 v77, v59 offset:15504
	ds_read_u16 v78, v59 offset:15776
	ds_read_u16 v79, v59 offset:16048
	ds_read_u16 v80, v59 offset:16320
	ds_read_u16 v81, v59 offset:16592
	ds_read_u16 v82, v59 offset:16864
	ds_read_u16 v83, v59 offset:17136
	ds_read_b128 v[20:23], v62 offset:19392
	ds_read_b128 v[24:27], v62 offset:19408
	ds_read_b128 v[28:31], v62 offset:19424
	ds_read_b128 v[32:35], v62 offset:19440
	s_waitcnt lgkmcnt(15)
	v_lshlrev_b32 v68, 16, v68
	s_waitcnt lgkmcnt(15)
	v_lshlrev_b32 v69, 16, v69
	s_waitcnt lgkmcnt(15)
	v_lshlrev_b32 v70, 16, v70
	s_waitcnt lgkmcnt(15)
	v_lshlrev_b32 v71, 16, v71
	s_waitcnt lgkmcnt(15)
	v_lshlrev_b32 v72, 16, v72
	s_waitcnt lgkmcnt(14)
	v_lshlrev_b32 v73, 16, v73
	s_waitcnt lgkmcnt(13)
	v_lshlrev_b32 v74, 16, v74
	s_waitcnt lgkmcnt(12)
	v_lshlrev_b32 v75, 16, v75
	s_waitcnt lgkmcnt(11)
	v_lshlrev_b32 v76, 16, v76
	s_waitcnt lgkmcnt(10)
	v_lshlrev_b32 v77, 16, v77
	s_waitcnt lgkmcnt(9)
	v_lshlrev_b32 v78, 16, v78
	s_waitcnt lgkmcnt(8)
	v_lshlrev_b32 v79, 16, v79
	s_waitcnt lgkmcnt(7)
	v_lshlrev_b32 v80, 16, v80
	s_waitcnt lgkmcnt(6)
	v_lshlrev_b32 v81, 16, v81
	s_waitcnt lgkmcnt(5)
	v_lshlrev_b32 v82, 16, v82
	s_waitcnt lgkmcnt(4)
	v_lshlrev_b32 v83, 16, v83
	s_waitcnt lgkmcnt(3)
	v_mul_f32 v68, v68, v20
	v_mul_f32 v69, v69, v21
	v_mul_f32 v70, v70, v22
	v_mul_f32 v71, v71, v23
	s_waitcnt lgkmcnt(2)
	v_mul_f32 v72, v72, v24
	v_mul_f32 v73, v73, v25
	v_mul_f32 v74, v74, v26
	v_mul_f32 v75, v75, v27
	s_waitcnt lgkmcnt(1)
	v_mul_f32 v76, v76, v28
	v_mul_f32 v77, v77, v29
	v_mul_f32 v78, v78, v30
	v_mul_f32 v79, v79, v31
	s_waitcnt lgkmcnt(0)
	v_mul_f32 v80, v80, v32
	v_mul_f32 v81, v81, v33
	v_mul_f32 v82, v82, v34
	v_mul_f32 v83, v83, v35
	ds_read_b128 v[20:23], v62 offset:19648
	ds_read_b128 v[24:27], v62 offset:19664
	ds_read_b128 v[28:31], v62 offset:19680
	ds_read_b128 v[32:35], v62 offset:19696
	v_mul_f32 v68, v68, v38
	v_mul_f32 v69, v69, v39
	v_mul_f32 v70, v70, v40
	v_mul_f32 v71, v71, v41
	v_mul_f32 v72, v72, v42
	v_mul_f32 v73, v73, v43
	v_mul_f32 v74, v74, v44
	v_mul_f32 v75, v75, v45
	v_mul_f32 v76, v76, v46
	v_mul_f32 v77, v77, v47
	v_mul_f32 v78, v78, v48
	v_mul_f32 v79, v79, v49
	v_mul_f32 v80, v80, v50
	v_mul_f32 v81, v81, v51
	v_mul_f32 v82, v82, v52
	v_mul_f32 v83, v83, v53
	s_waitcnt lgkmcnt(3)
	v_fma_f32 v68, v68, v20, -v2
	v_fma_f32 v69, v69, v21, -v3
	v_fma_f32 v70, v70, v22, -v4
	v_fma_f32 v71, v71, v23, -v5
	s_waitcnt lgkmcnt(2)
	v_fma_f32 v72, v72, v24, -v6
	v_fma_f32 v73, v73, v25, -v7
	v_fma_f32 v74, v74, v26, -v8
	v_fma_f32 v75, v75, v27, -v9
	s_waitcnt lgkmcnt(1)
	v_fma_f32 v76, v76, v28, -v10
	v_fma_f32 v77, v77, v29, -v11
	v_fma_f32 v78, v78, v30, -v12
	v_fma_f32 v79, v79, v31, -v13
	s_waitcnt lgkmcnt(0)
	v_fma_f32 v80, v80, v32, -v14
	v_fma_f32 v81, v81, v33, -v15
	v_fma_f32 v82, v82, v34, -v16
	v_fma_f32 v83, v83, v35, -v17
	ds_read_b128 v[38:41], v62 offset:13520
	ds_read_b128 v[20:23], v62 offset:13792
	s_waitcnt lgkmcnt(1)
	v_fma_f32 v69, -v38, v68, v69
	ds_read_b128 v[38:41], v62 offset:14064
	s_waitcnt lgkmcnt(1)
	v_fma_f32 v70, -v20, v68, v70
	v_fma_f32 v70, -v21, v69, v70
	ds_read_b128 v[20:23], v62 offset:14336
	s_waitcnt lgkmcnt(1)
	v_fma_f32 v71, -v38, v68, v71
	v_fma_f32 v71, -v39, v69, v71
	v_fma_f32 v71, -v40, v70, v71
	ds_read_b128 v[38:41], v62 offset:14608
	ds_read_b128 v[42:45], v62 offset:14624
	s_waitcnt lgkmcnt(2)
	v_fma_f32 v72, -v20, v68, v72
	v_fma_f32 v72, -v21, v69, v72
	v_fma_f32 v72, -v22, v70, v72
	v_fma_f32 v72, -v23, v71, v72
	ds_read_b128 v[20:23], v62 offset:14880
	ds_read_b128 v[24:27], v62 offset:14896
	s_waitcnt lgkmcnt(3)
	v_fma_f32 v73, -v38, v68, v73
	v_fma_f32 v73, -v39, v69, v73
	v_fma_f32 v73, -v40, v70, v73
	v_fma_f32 v73, -v41, v71, v73
	s_waitcnt lgkmcnt(2)
	v_fma_f32 v73, -v42, v72, v73
	ds_read_b128 v[38:41], v62 offset:15152
	ds_read_b128 v[42:45], v62 offset:15168
	s_waitcnt lgkmcnt(3)
	v_fma_f32 v74, -v20, v68, v74
	v_fma_f32 v74, -v21, v69, v74
	v_fma_f32 v74, -v22, v70, v74
	v_fma_f32 v74, -v23, v71, v74
	s_waitcnt lgkmcnt(2)
	v_fma_f32 v74, -v24, v72, v74
	v_fma_f32 v74, -v25, v73, v74
	ds_read_b128 v[20:23], v62 offset:15424
	ds_read_b128 v[24:27], v62 offset:15440
	s_waitcnt lgkmcnt(3)
	v_fma_f32 v75, -v38, v68, v75
	v_fma_f32 v75, -v39, v69, v75
	v_fma_f32 v75, -v40, v70, v75
	v_fma_f32 v75, -v41, v71, v75
	s_waitcnt lgkmcnt(2)
	v_fma_f32 v75, -v42, v72, v75
	v_fma_f32 v75, -v43, v73, v75
	v_fma_f32 v75, -v44, v74, v75
	ds_read_b128 v[38:41], v62 offset:15696
	ds_read_b128 v[42:45], v62 offset:15712
	ds_read_b128 v[46:49], v62 offset:15728
	s_waitcnt lgkmcnt(4)
	v_fma_f32 v76, -v20, v68, v76
	v_fma_f32 v76, -v21, v69, v76
	v_fma_f32 v76, -v22, v70, v76
	v_fma_f32 v76, -v23, v71, v76
	s_waitcnt lgkmcnt(3)
	v_fma_f32 v76, -v24, v72, v76
	v_fma_f32 v76, -v25, v73, v76
	v_fma_f32 v76, -v26, v74, v76
	v_fma_f32 v76, -v27, v75, v76
	ds_read_b128 v[20:23], v62 offset:15968
	ds_read_b128 v[24:27], v62 offset:15984
	ds_read_b128 v[28:31], v62 offset:16000
	s_waitcnt lgkmcnt(5)
	v_fma_f32 v77, -v38, v68, v77
	v_fma_f32 v77, -v39, v69, v77
	v_fma_f32 v77, -v40, v70, v77
	v_fma_f32 v77, -v41, v71, v77
	s_waitcnt lgkmcnt(4)
	v_fma_f32 v77, -v42, v72, v77
	v_fma_f32 v77, -v43, v73, v77
	v_fma_f32 v77, -v44, v74, v77
	v_fma_f32 v77, -v45, v75, v77
	s_waitcnt lgkmcnt(3)
	v_fma_f32 v77, -v46, v76, v77
	ds_read_b128 v[38:41], v62 offset:16240
	ds_read_b128 v[42:45], v62 offset:16256
	ds_read_b128 v[46:49], v62 offset:16272
	s_waitcnt lgkmcnt(5)
	v_fma_f32 v78, -v20, v68, v78
	v_fma_f32 v78, -v21, v69, v78
	v_fma_f32 v78, -v22, v70, v78
	v_fma_f32 v78, -v23, v71, v78
	s_waitcnt lgkmcnt(4)
	v_fma_f32 v78, -v24, v72, v78
	v_fma_f32 v78, -v25, v73, v78
	v_fma_f32 v78, -v26, v74, v78
	v_fma_f32 v78, -v27, v75, v78
	s_waitcnt lgkmcnt(3)
	v_fma_f32 v78, -v28, v76, v78
	v_fma_f32 v78, -v29, v77, v78
	ds_read_b128 v[20:23], v62 offset:16512
	ds_read_b128 v[24:27], v62 offset:16528
	ds_read_b128 v[28:31], v62 offset:16544
	s_waitcnt lgkmcnt(5)
	v_fma_f32 v79, -v38, v68, v79
	v_fma_f32 v79, -v39, v69, v79
	v_fma_f32 v79, -v40, v70, v79
	v_fma_f32 v79, -v41, v71, v79
	s_waitcnt lgkmcnt(4)
	v_fma_f32 v79, -v42, v72, v79
	v_fma_f32 v79, -v43, v73, v79
	v_fma_f32 v79, -v44, v74, v79
	v_fma_f32 v79, -v45, v75, v79
	s_waitcnt lgkmcnt(3)
	v_fma_f32 v79, -v46, v76, v79
	v_fma_f32 v79, -v47, v77, v79
	v_fma_f32 v79, -v48, v78, v79
	ds_read_b128 v[38:41], v62 offset:16784
	ds_read_b128 v[42:45], v62 offset:16800
	ds_read_b128 v[46:49], v62 offset:16816
	ds_read_b128 v[50:53], v62 offset:16832
	s_waitcnt lgkmcnt(6)
	v_fma_f32 v80, -v20, v68, v80
	v_fma_f32 v80, -v21, v69, v80
	v_fma_f32 v80, -v22, v70, v80
	v_fma_f32 v80, -v23, v71, v80
	s_waitcnt lgkmcnt(5)
	v_fma_f32 v80, -v24, v72, v80
	v_fma_f32 v80, -v25, v73, v80
	v_fma_f32 v80, -v26, v74, v80
	v_fma_f32 v80, -v27, v75, v80
	s_waitcnt lgkmcnt(4)
	v_fma_f32 v80, -v28, v76, v80
	v_fma_f32 v80, -v29, v77, v80
	v_fma_f32 v80, -v30, v78, v80
	v_fma_f32 v80, -v31, v79, v80
	ds_read_b128 v[20:23], v62 offset:17056
	ds_read_b128 v[24:27], v62 offset:17072
	ds_read_b128 v[28:31], v62 offset:17088
	ds_read_b128 v[32:35], v62 offset:17104
	s_waitcnt lgkmcnt(7)
	v_fma_f32 v81, -v38, v68, v81
	v_fma_f32 v81, -v39, v69, v81
	v_fma_f32 v81, -v40, v70, v81
	v_fma_f32 v81, -v41, v71, v81
	s_waitcnt lgkmcnt(6)
	v_fma_f32 v81, -v42, v72, v81
	v_fma_f32 v81, -v43, v73, v81
	v_fma_f32 v81, -v44, v74, v81
	v_fma_f32 v81, -v45, v75, v81
	s_waitcnt lgkmcnt(5)
	v_fma_f32 v81, -v46, v76, v81
	v_fma_f32 v81, -v47, v77, v81
	v_fma_f32 v81, -v48, v78, v81
	v_fma_f32 v81, -v49, v79, v81
	s_waitcnt lgkmcnt(4)
	v_fma_f32 v81, -v50, v80, v81
	ds_read_b128 v[38:41], v62 offset:17328
	ds_read_b128 v[42:45], v62 offset:17344
	ds_read_b128 v[46:49], v62 offset:17360
	ds_read_b128 v[50:53], v62 offset:17376
	s_waitcnt lgkmcnt(7)
	v_fma_f32 v82, -v20, v68, v82
	v_fma_f32 v82, -v21, v69, v82
	v_fma_f32 v82, -v22, v70, v82
	v_fma_f32 v82, -v23, v71, v82
	s_waitcnt lgkmcnt(6)
	v_fma_f32 v82, -v24, v72, v82
	v_fma_f32 v82, -v25, v73, v82
	v_fma_f32 v82, -v26, v74, v82
	v_fma_f32 v82, -v27, v75, v82
	s_waitcnt lgkmcnt(5)
	v_fma_f32 v82, -v28, v76, v82
	v_fma_f32 v82, -v29, v77, v82
	v_fma_f32 v82, -v30, v78, v82
	v_fma_f32 v82, -v31, v79, v82
	s_waitcnt lgkmcnt(4)
	v_fma_f32 v82, -v32, v80, v82
	v_fma_f32 v82, -v33, v81, v82
	s_waitcnt lgkmcnt(3)
	v_fma_f32 v83, -v38, v68, v83
	v_fma_f32 v83, -v39, v69, v83
	v_fma_f32 v83, -v40, v70, v83
	v_fma_f32 v83, -v41, v71, v83
	s_waitcnt lgkmcnt(2)
	v_fma_f32 v83, -v42, v72, v83
	v_fma_f32 v83, -v43, v73, v83
	v_fma_f32 v83, -v44, v74, v83
	v_fma_f32 v83, -v45, v75, v83
	s_waitcnt lgkmcnt(1)
	v_fma_f32 v83, -v46, v76, v83
	v_fma_f32 v83, -v47, v77, v83
	v_fma_f32 v83, -v48, v78, v83
	v_fma_f32 v83, -v49, v79, v83
	s_waitcnt lgkmcnt(0)
	v_fma_f32 v83, -v50, v80, v83
	v_fma_f32 v83, -v51, v81, v83
	v_fma_f32 v83, -v52, v82, v83
	v_add_u32 v64, 0xc000, v61
	v_cvt_pk_bf16_f32 v2, v68, v68
	global_store_short v64, v2, s[36:37] offset:0
	v_cvt_pk_bf16_f32 v3, v69, v69
	global_store_short v64, v3, s[36:37] offset:1024
	v_cvt_pk_bf16_f32 v4, v70, v70
	global_store_short v64, v4, s[36:37] offset:2048
	v_cvt_pk_bf16_f32 v5, v71, v71
	global_store_short v64, v5, s[36:37] offset:3072
	v_add_u32 v64, 0xd000, v61
	v_cvt_pk_bf16_f32 v6, v72, v72
	global_store_short v64, v6, s[36:37] offset:0
	v_cvt_pk_bf16_f32 v7, v73, v73
	global_store_short v64, v7, s[36:37] offset:1024
	v_cvt_pk_bf16_f32 v8, v74, v74
	global_store_short v64, v8, s[36:37] offset:2048
	v_cvt_pk_bf16_f32 v9, v75, v75
	global_store_short v64, v9, s[36:37] offset:3072
	v_add_u32 v64, 0xe000, v61
	v_cvt_pk_bf16_f32 v2, v76, v76
	global_store_short v64, v2, s[36:37] offset:0
	v_cvt_pk_bf16_f32 v3, v77, v77
	global_store_short v64, v3, s[36:37] offset:1024
	v_cvt_pk_bf16_f32 v4, v78, v78
	global_store_short v64, v4, s[36:37] offset:2048
	v_cvt_pk_bf16_f32 v5, v79, v79
	global_store_short v64, v5, s[36:37] offset:3072
	v_add_u32 v64, 0xf000, v61
	v_cvt_pk_bf16_f32 v6, v80, v80
	global_store_short v64, v6, s[36:37] offset:0
	v_cvt_pk_bf16_f32 v7, v81, v81
	global_store_short v64, v7, s[36:37] offset:1024
	v_cvt_pk_bf16_f32 v8, v82, v82
	global_store_short v64, v8, s[36:37] offset:2048
	v_cvt_pk_bf16_f32 v9, v83, v83
	global_store_short v64, v9, s[36:37] offset:3072
	s_waitcnt lgkmcnt(0)
	s_branch .LBB0_339
